# GDN scan redesigned: 8-token groups, in-group triangular solve and output mix as 2 f32 MFMAs with precomputed (I+L)^-1 and MQ*T from the coefficient pass; no look-ahead pairing
# speedup vs baseline: 1.0092x; 1.0092x over previous
.LBB0_537:
	v_mov_b32_e32 v112, v1
	s_waitcnt vmcnt(6)
	v_lshlrev_b32_e32 v24, 16, v2
	v_lshlrev_b32_e32 v38, 3, v112
	v_and_b32_e32 v23, 0x78, v38
	v_lshl_add_u32 v32, v23, 2, 0
	v_ashrrev_i32_e32 v22, 4, v112
	v_and_b32_e32 v25, 0xffff0000, v2
	v_lshlrev_b32_e32 v26, 16, v3
	v_and_b32_e32 v27, 0xffff0000, v3
	v_lshlrev_b32_e32 v28, 16, v4
	v_and_b32_e32 v29, 0xffff0000, v4
	v_lshlrev_b32_e32 v30, 16, v5
	v_and_b32_e32 v31, 0xffff0000, v5
	v_pk_mul_f32 v[26:27], v[26:27], s[74:75] op_sel_hi:[1,0]
	v_pk_mul_f32 v[24:25], v[24:25], s[74:75] op_sel_hi:[1,0]
	v_mad_u64_u32 v[34:35], s[0:1], v22, s84, v[32:33]
	ds_write_b128 v34, v[24:27]
	v_pk_mul_f32 v[26:27], v[30:31], s[74:75] op_sel_hi:[1,0]
	v_pk_mul_f32 v[24:25], v[28:29], s[74:75] op_sel_hi:[1,0]
	ds_write_b128 v34, v[24:27] offset:16
	s_waitcnt vmcnt(5)
	v_lshlrev_b32_e32 v24, 16, v6
	v_and_b32_e32 v25, 0xffff0000, v6
	v_lshlrev_b32_e32 v26, 16, v7
	v_and_b32_e32 v27, 0xffff0000, v7
	v_lshlrev_b32_e32 v28, 16, v8
	v_and_b32_e32 v29, 0xffff0000, v8
	v_add_u32_e32 v113, 0x200, v112
	v_lshlrev_b32_e32 v30, 16, v9
	v_and_b32_e32 v31, 0xffff0000, v9
	ds_write_b128 v34, v[24:27] offset:33792
	ds_write_b128 v34, v[28:31] offset:33808
	v_ashrrev_i32_e32 v24, 4, v113
	s_waitcnt vmcnt(4)
	v_lshlrev_b32_e32 v26, 16, v10
	v_and_b32_e32 v27, 0xffff0000, v10
	v_lshlrev_b32_e32 v28, 16, v11
	v_and_b32_e32 v29, 0xffff0000, v11
	v_lshlrev_b32_e32 v30, 16, v12
	v_and_b32_e32 v31, 0xffff0000, v12
	v_lshlrev_b32_e32 v34, 16, v13
	v_and_b32_e32 v35, 0xffff0000, v13
	v_pk_mul_f32 v[28:29], v[28:29], s[74:75] op_sel_hi:[1,0]
	v_pk_mul_f32 v[26:27], v[26:27], s[74:75] op_sel_hi:[1,0]
	v_mad_u64_u32 v[36:37], s[0:1], v24, s84, v[32:33]
	ds_write_b128 v36, v[26:29]
	v_pk_mul_f32 v[28:29], v[34:35], s[74:75] op_sel_hi:[1,0]
	v_pk_mul_f32 v[26:27], v[30:31], s[74:75] op_sel_hi:[1,0]
	ds_write_b128 v36, v[26:29] offset:16
	s_waitcnt vmcnt(3)
	v_lshlrev_b32_e32 v26, 16, v14
	v_and_b32_e32 v27, 0xffff0000, v14
	v_lshlrev_b32_e32 v28, 16, v15
	v_and_b32_e32 v29, 0xffff0000, v15
	v_lshlrev_b32_e32 v30, 16, v16
	v_and_b32_e32 v31, 0xffff0000, v16
	v_lshlrev_b32_e32 v32, 16, v17
	v_and_b32_e32 v33, 0xffff0000, v17
	ds_write_b128 v36, v[26:29] offset:33792
	ds_write_b128 v36, v[30:33] offset:33808
	v_ashrrev_i32_e32 v26, 3, v112
	v_and_b32_e32 v28, 56, v38
	v_lshlrev_b32_e32 v25, 8, v26
	v_lshlrev_b32_e32 v27, 2, v28
	s_waitcnt vmcnt(2)
	v_lshlrev_b32_e32 v30, 16, v18
	v_and_b32_e32 v31, 0xffff0000, v18
	v_lshlrev_b32_e32 v32, 16, v19
	v_and_b32_e32 v33, 0xffff0000, v19
	v_add3_u32 v25, s85, v25, v27
	v_cmp_gt_i32_e32 vcc, 64, v112
	v_and_b32_e32 v95, 3, v112
	v_lshlrev_b32_e32 v34, 16, v20
	v_and_b32_e32 v35, 0xffff0000, v20
	v_lshlrev_b32_e32 v36, 16, v21
	v_and_b32_e32 v37, 0xffff0000, v21
	ds_write_b128 v25, v[30:33]
	ds_write_b128 v25, v[34:37] offset:16
	s_and_saveexec_b64 s[0:1], vcc
	s_cbranch_execz .LBB0_539
	s_waitcnt vmcnt(0)
	v_add_f32_e32 v25, v124, v127
	s_mov_b32 s3, 0xbfb8aa3b
	v_mul_f32_e64 v27, |v25|, s3
	v_exp_f32_e32 v27, v27
	s_mov_b32 s3, 0x3f2aaaab
	v_max_f32_e32 v25, 0, v25
	v_mul_f32_e32 v29, 0xbfb8aa3b, v126
	v_add_f32_e32 v32, 1.0, v27
	v_add_f32_e32 v30, -1.0, v32
	v_sub_f32_e32 v31, v30, v32
	v_add_f32_e32 v31, 1.0, v31
	v_sub_f32_e32 v30, v27, v30
	v_add_f32_e32 v33, v30, v31
	v_frexp_mant_f32_e32 v34, v32
	v_cvt_f64_f32_e32 v[30:31], v32
	v_frexp_exp_i32_f64_e32 v30, v[30:31]
	v_cmp_gt_f32_e32 vcc, s3, v34
	s_mov_b32 s3, 0x3f317218
	v_exp_f32_e32 v29, v29
	v_subbrev_co_u32_e32 v30, vcc, 0, v30, vcc
	v_sub_u32_e32 v31, 0, v30
	v_ldexp_f32 v32, v32, v31
	v_ldexp_f32 v31, v33, v31
	v_add_f32_e32 v33, -1.0, v32
	v_add_f32_e32 v36, 1.0, v32
	v_add_f32_e32 v34, 1.0, v33
	v_add_f32_e32 v37, -1.0, v36
	v_sub_f32_e32 v34, v32, v34
	v_sub_f32_e32 v32, v32, v37
	v_add_f32_e32 v34, v31, v34
	v_add_f32_e32 v31, v31, v32
	v_add_f32_e32 v32, v36, v31
	v_rcp_f32_e32 v37, v32
	v_add_f32_e32 v35, v33, v34
	v_sub_f32_e32 v33, v35, v33
	v_sub_f32_e32 v33, v34, v33
	v_sub_f32_e32 v34, v32, v36
	v_sub_f32_e32 v31, v31, v34
	v_mul_f32_e32 v34, v35, v37
	v_mul_f32_e32 v36, v32, v34
	v_fma_f32 v38, v34, v32, -v36
	v_fmac_f32_e32 v38, v34, v31
	v_add_f32_e32 v39, v36, v38
	v_sub_f32_e32 v40, v35, v39
	v_sub_f32_e32 v35, v35, v40
	v_sub_f32_e32 v36, v39, v36
	v_sub_f32_e32 v35, v35, v39
	v_add_f32_e32 v33, v33, v35
	v_sub_f32_e32 v35, v36, v38
	v_add_f32_e32 v33, v35, v33
	v_add_f32_e32 v35, v40, v33
	v_mul_f32_e32 v36, v37, v35
	v_mul_f32_e32 v38, v32, v36
	v_fma_f32 v32, v36, v32, -v38
	v_fmac_f32_e32 v32, v36, v31
	v_sub_f32_e32 v31, v40, v35
	v_add_f32_e32 v31, v33, v31
	v_add_f32_e32 v33, v38, v32
	v_sub_f32_e32 v39, v35, v33
	v_sub_f32_e32 v35, v35, v39
	v_sub_f32_e32 v38, v33, v38
	v_sub_f32_e32 v33, v35, v33
	v_add_f32_e32 v31, v31, v33
	v_sub_f32_e32 v32, v38, v32
	v_cvt_f32_i32_e32 v30, v30
	v_add_f32_e32 v31, v32, v31
	v_add_f32_e32 v32, v34, v36
	v_add_f32_e32 v31, v39, v31
	v_sub_f32_e32 v33, v32, v34
	v_mul_f32_e32 v31, v37, v31
	v_sub_f32_e32 v33, v36, v33
	v_add_f32_e32 v31, v33, v31
	v_mul_f32_e32 v36, 0x3f317218, v30
	v_add_f32_e32 v33, v32, v31
	v_fma_f32 v37, v30, s3, -v36
	v_mul_f32_e32 v34, v33, v33
	v_fmac_f32_e32 v37, 0xb102e308, v30
	v_sub_f32_e32 v30, v33, v32
	v_fmamk_f32 v35, v34, 0x3e9b6dac, v118
	v_sub_f32_e32 v30, v31, v30
	v_add_f32_e32 v31, v36, v37
	v_fmaak_f32 v35, v34, v35, 0x3f2aaada
	v_sub_f32_e32 v32, v31, v36
	v_ldexp_f32 v36, v33, 1
	v_mul_f32_e32 v33, v33, v34
	v_mul_f32_e32 v33, v33, v35
	v_add_f32_e32 v34, v36, v33
	v_sub_f32_e32 v35, v34, v36
	v_ldexp_f32 v30, v30, 1
	v_sub_f32_e32 v33, v33, v35
	v_add_f32_e32 v30, v30, v33
	v_add_f32_e32 v33, v34, v30
	v_sub_f32_e32 v34, v33, v34
	v_sub_f32_e32 v30, v30, v34
	v_add_f32_e32 v34, v31, v33
	v_sub_f32_e32 v35, v34, v31
	v_sub_f32_e32 v36, v34, v35
	v_sub_f32_e32 v32, v37, v32
	v_sub_f32_e32 v31, v31, v36
	v_sub_f32_e32 v33, v33, v35
	v_add_f32_e32 v31, v33, v31
	v_add_f32_e32 v33, v32, v30
	v_sub_f32_e32 v35, v33, v32
	v_sub_f32_e32 v36, v33, v35
	v_sub_f32_e32 v32, v32, v36
	v_sub_f32_e32 v30, v30, v35
	v_add_f32_e32 v31, v33, v31
	v_add_f32_e32 v30, v30, v32
	v_add_f32_e32 v32, v34, v31
	v_sub_f32_e32 v33, v32, v34
	v_sub_f32_e32 v31, v31, v33
	v_add_f32_e32 v30, v30, v31
	s_mov_b32 s3, 0x7f800000
	v_add_f32_e32 v30, v32, v30
	v_cmp_neq_f32_e32 vcc, s3, v27
	s_mov_b32 s3, 0x33800000
	v_and_b32_e32 v31, 64, v122
	v_cndmask_b32_e32 v30, v119, v30, vcc
	v_cmp_ngt_f32_e32 vcc, -1.0, v27
	v_add_f32_e32 v29, 1.0, v29
	v_rcp_f32_e32 v29, v29
	v_cndmask_b32_e32 v30, v120, v30, vcc
	v_cmp_neq_f32_e32 vcc, -1.0, v27
	s_nop 1
	v_cndmask_b32_e32 v30, v121, v30, vcc
	v_cmp_lt_f32_e64 vcc, |v27|, s3
	s_nop 1
	v_cndmask_b32_e32 v27, v30, v27, vcc
	v_add_u32_e32 v30, -1, v122
	v_cmp_lt_i32_e32 vcc, v30, v31
	v_add_f32_e32 v25, v25, v27
	v_mul_f32_e64 v27, v25, -v125
	v_cndmask_b32_e32 v30, v30, v122, vcc
	v_lshlrev_b32_e32 v30, 2, v30
	ds_bpermute_b32 v30, v30, v27
	v_cmp_eq_u32_e32 vcc, 0, v95
	s_waitcnt lgkmcnt(0)
	v_fma_f32 v25, v25, -v125, v30
	v_cndmask_b32_e32 v25, v25, v27, vcc
	v_add_u32_e32 v27, -2, v122
	v_cmp_lt_i32_e32 vcc, v27, v31
	v_lshl_add_u32 v30, v112, 2, 0
	v_add_u32_e32 v32, 0x21900, v30
	v_cndmask_b32_e32 v27, v27, v122, vcc
	v_lshlrev_b32_e32 v27, 2, v27
	ds_bpermute_b32 v27, v27, v25
	v_cmp_gt_u32_e32 vcc, 2, v95
	ds_write_b32 v32, v29
	v_add_u32_e32 v29, 0x21800, v30
	s_waitcnt lgkmcnt(1)
	v_add_f32_e32 v27, v25, v27
	v_cndmask_b32_e32 v25, v27, v25, vcc
	v_and_or_b32 v27, v112, 56, v31
	v_lshlrev_b32_e32 v27, 2, v27
	ds_bpermute_b32 v33, v27, v25 offset:12
	v_and_b32_e32 v34, 4, v112
	v_cmp_ne_u32_e32 vcc, 0, v34
	s_waitcnt lgkmcnt(0)
	v_add_f32_e32 v33, v25, v33
	v_cndmask_b32_e32 v25, v25, v33, vcc
	ds_bpermute_b32 v27, v27, v25 offset:28
	ds_write_b32 v29, v25
	v_mul_f32_e32 v29, 0x3fb8aa3b, v25
	v_exp_f32_e32 v29, v29
	s_waitcnt lgkmcnt(1)
	v_sub_f32_e32 v25, v27, v25
	v_mul_f32_e32 v25, 0x3fb8aa3b, v25
	v_exp_f32_e32 v25, v25
	v_add_u32_e32 v27, 0x21a00, v30
	ds_write_b32 v27, v29
	v_add_u32_e32 v27, 0x21b00, v30
	ds_write_b32 v27, v25
.LBB0_539:
	s_or_b64 exec, exec, s[0:1]
	v_bfe_u32 v25, v112, 1, 4
	v_subrev_co_u32_e32 v27, vcc, 10, v25
	s_xor_b64 s[4:5], vcc, -1
	s_waitcnt lgkmcnt(0)
	s_barrier
	v_and_b32_e32 v150, 15, v180
	v_bfe_u32 v151, v180, 4, 2
	v_lshrrev_b32_e32 v152, 6, v180
	v_and_b32_e32 v157, 7, v150
	v_lshl_add_u32 v153, v152, 3, v157
	v_mul_u32_u24_e32 v153, 0x210, v153
	v_lshl_add_u32 v133, v151, 4, v153
	v_and_b32_e32 v154, 8, v150
	v_sub_u32_e32 v154, 8, v154
	v_mul_u32_u24_e32 v154, 0x1080, v154
	v_add_u32_e32 v132, v133, v154
	v_add_u32_e32 v133, 0x8400, v133
	ds_read_b128 v[30:33], v132 offset:0
	ds_read_b128 v[62:65], v133 offset:0
	ds_read_b128 v[34:37], v132 offset:64
	ds_read_b128 v[66:69], v133 offset:64
	ds_read_b128 v[38:41], v132 offset:128
	ds_read_b128 v[70:73], v133 offset:128
	ds_read_b128 v[42:45], v132 offset:192
	ds_read_b128 v[74:77], v133 offset:192
	ds_read_b128 v[46:49], v132 offset:256
	ds_read_b128 v[78:81], v133 offset:256
	ds_read_b128 v[50:53], v132 offset:320
	ds_read_b128 v[82:85], v133 offset:320
	ds_read_b128 v[54:57], v132 offset:384
	ds_read_b128 v[86:89], v133 offset:384
	ds_read_b128 v[58:61], v132 offset:448
	ds_read_b128 v[90:93], v133 offset:448
	v_lshrrev_b32_e32 v155, 1, v151
	v_and_b32_e32 v156, 1, v151
	v_lshl_add_u32 v153, v152, 1, v156
	v_lshlrev_b32_e32 v135, 4, v153
	v_add_u32_e32 v137, 0x21900, v135
	v_add_u32_e32 v135, 0x21800, v135
	v_lshl_add_u32 v136, v152, 3, v157
	v_lshlrev_b32_e32 v136, 2, v136
	v_add_u32_e32 v136, 0x21800, v136
	ds_read_b128 v[140:143], v135
	ds_read_b128 v[144:147], v137
	ds_read_b32 v148, v136
	v_lshl_add_u32 v134, v152, 1, v155
	v_lshlrev_b32_e32 v134, 8, v134
	v_lshl_add_u32 v134, v156, 7, v134
	v_lshl_add_u32 v134, v157, 2, v134
	v_add_u32_e32 v134, 0x14800, v134
	v_sub_u32_e32 v154, 1, v155
	v_add_u32_e32 v158, v157, v154
	v_lshlrev_b32_e32 v153, 2, v156
	v_sub_u32_e32 v158, v158, v153
	v_mov_b32_e32 v160, 1.0
	v_cmp_eq_u32_e64 s[80:81], 1, v155
	v_cmp_ge_i32_e64 s[0:1], 1, v158
	v_cmp_ge_i32_e64 s[4:5], 2, v158
	v_cmp_ge_i32_e64 s[6:7], 3, v158
	v_cmp_ge_i32_e32 vcc, 0, v158
	s_waitcnt lgkmcnt(0)
	v_mfma_f32_16x16x4_f32 v[96:99], v30, v62, 0
	v_mfma_f32_16x16x4_f32 v[100:103], v31, v63, 0
	v_mfma_f32_16x16x4_f32 v[96:99], v32, v64, v[96:99]
	v_mfma_f32_16x16x4_f32 v[100:103], v33, v65, v[100:103]
	v_sub_f32_e32 v164, v140, v148
	v_sub_f32_e32 v165, v141, v148
	v_sub_f32_e32 v166, v142, v148
	v_sub_f32_e32 v167, v143, v148
	v_min_f32_e32 v164, 0, v164
	v_min_f32_e32 v165, 0, v165
	v_min_f32_e32 v166, 0, v166
	v_min_f32_e32 v167, 0, v167
	v_mul_f32_e32 v164, 0x3fb8aa3b, v164
	v_mul_f32_e32 v165, 0x3fb8aa3b, v165
	v_mul_f32_e32 v166, 0x3fb8aa3b, v166
	v_mul_f32_e32 v167, 0x3fb8aa3b, v167
	v_exp_f32_e32 v164, v164
	v_exp_f32_e32 v165, v165
	v_exp_f32_e32 v166, v166
	v_exp_f32_e32 v167, v167
	v_mfma_f32_16x16x4_f32 v[96:99], v34, v66, v[96:99]
	v_mfma_f32_16x16x4_f32 v[100:103], v35, v67, v[100:103]
	v_mfma_f32_16x16x4_f32 v[96:99], v36, v68, v[96:99]
	v_mfma_f32_16x16x4_f32 v[100:103], v37, v69, v[100:103]
	v_cndmask_b32_e64 v144, v144, v160, s[80:81]
	v_cndmask_b32_e64 v145, v145, v160, s[80:81]
	v_cndmask_b32_e64 v146, v146, v160, s[80:81]
	v_cndmask_b32_e64 v147, v147, v160, s[80:81]
	v_mul_f32_e32 v164, v164, v144
	v_mul_f32_e32 v165, v165, v145
	v_mul_f32_e32 v166, v166, v146
	v_mul_f32_e32 v167, v167, v147
	v_cndmask_b32_e32 v164, 0, v164, vcc
	v_cndmask_b32_e64 v165, 0, v165, s[0:1]
	v_cndmask_b32_e64 v166, 0, v166, s[4:5]
	v_cndmask_b32_e64 v167, 0, v167, s[6:7]
	v_mfma_f32_16x16x4_f32 v[96:99], v38, v70, v[96:99]
	v_mfma_f32_16x16x4_f32 v[100:103], v39, v71, v[100:103]
	v_mfma_f32_16x16x4_f32 v[96:99], v40, v72, v[96:99]
	v_mfma_f32_16x16x4_f32 v[100:103], v41, v73, v[100:103]
	v_mfma_f32_16x16x4_f32 v[96:99], v42, v74, v[96:99]
	v_mfma_f32_16x16x4_f32 v[100:103], v43, v75, v[100:103]
	v_mfma_f32_16x16x4_f32 v[96:99], v44, v76, v[96:99]
	v_mfma_f32_16x16x4_f32 v[100:103], v45, v77, v[100:103]
	v_mfma_f32_16x16x4_f32 v[96:99], v46, v78, v[96:99]
	v_mfma_f32_16x16x4_f32 v[100:103], v47, v79, v[100:103]
	v_mfma_f32_16x16x4_f32 v[96:99], v48, v80, v[96:99]
	v_mfma_f32_16x16x4_f32 v[100:103], v49, v81, v[100:103]
	v_mfma_f32_16x16x4_f32 v[96:99], v50, v82, v[96:99]
	v_mfma_f32_16x16x4_f32 v[100:103], v51, v83, v[100:103]
	v_mfma_f32_16x16x4_f32 v[96:99], v52, v84, v[96:99]
	v_mfma_f32_16x16x4_f32 v[100:103], v53, v85, v[100:103]
	v_mfma_f32_16x16x4_f32 v[96:99], v54, v86, v[96:99]
	v_mfma_f32_16x16x4_f32 v[100:103], v55, v87, v[100:103]
	v_mfma_f32_16x16x4_f32 v[96:99], v56, v88, v[96:99]
	v_mfma_f32_16x16x4_f32 v[100:103], v57, v89, v[100:103]
	v_mfma_f32_16x16x4_f32 v[96:99], v58, v90, v[96:99]
	v_mfma_f32_16x16x4_f32 v[100:103], v59, v91, v[100:103]
	v_mfma_f32_16x16x4_f32 v[96:99], v60, v92, v[96:99]
	v_mfma_f32_16x16x4_f32 v[100:103], v61, v93, v[100:103]
	s_nop 7
	s_nop 2
	v_pk_add_f32 v[96:97], v[96:97], v[100:101]
	v_pk_add_f32 v[98:99], v[98:99], v[102:103]
	v_mul_f32_e32 v96, v96, v164
	v_mul_f32_e32 v97, v97, v165
	v_mul_f32_e32 v98, v98, v166
	v_mul_f32_e32 v99, v99, v167
	ds_write_b32 v134, v96 offset:0
	ds_write_b32 v134, v97 offset:32
	ds_write_b32 v134, v98 offset:64
	ds_write_b32 v134, v99 offset:96
	v_lshlrev_b32_e32 v135, 9, v152
	v_add_u32_e32 v135, 0x14800, v135
	v_lshlrev_b32_e32 v136, 5, v152
	v_add_u32_e32 v136, 0x21b00, v136
	v_lshl_add_u32 v137, v157, 2, v135
	ds_read_b128 v[30:33], v135 offset:32
	ds_read_b128 v[34:37], v135 offset:64
	ds_read_b128 v[38:41], v135 offset:96
	ds_read_b128 v[42:45], v135 offset:128
	ds_read_b128 v[50:53], v135 offset:160
	ds_read_b128 v[54:57], v135 offset:176
	ds_read_b128 v[58:61], v135 offset:192
	ds_read_b128 v[62:65], v135 offset:208
	ds_read_b128 v[66:69], v135 offset:224
	ds_read_b128 v[70:73], v135 offset:240
	ds_read_b128 v[74:77], v135 offset:256
	ds_read_b128 v[78:81], v135 offset:288
	ds_read_b128 v[82:85], v135 offset:320
	ds_read_b128 v[86:89], v135 offset:352
	ds_read_b128 v[216:219], v135 offset:384
	ds_read_b128 v[220:223], v135 offset:400
	ds_read_b128 v[224:227], v135 offset:416
	ds_read_b128 v[228:231], v135 offset:432
	ds_read_b128 v[140:143], v135 offset:448
	ds_read_b128 v[144:147], v135 offset:464
	ds_read_b128 v[162:165], v135 offset:480
	ds_read_b128 v[166:169], v135 offset:496
	ds_read_b128 v[104:107], v136
	ds_read_b128 v[108:111], v136 offset:16
	v_cmp_eq_u32_e32 vcc, 0, v157
	v_cndmask_b32_e32 v96, 0, v160, vcc
	v_cmp_eq_u32_e32 vcc, 1, v157
	v_cndmask_b32_e32 v97, 0, v160, vcc
	v_cmp_eq_u32_e32 vcc, 2, v157
	v_cndmask_b32_e32 v98, 0, v160, vcc
	v_cmp_eq_u32_e32 vcc, 3, v157
	v_cndmask_b32_e32 v99, 0, v160, vcc
	v_cmp_eq_u32_e32 vcc, 4, v157
	v_cndmask_b32_e32 v100, 0, v160, vcc
	v_cmp_eq_u32_e32 vcc, 5, v157
	v_cndmask_b32_e32 v101, 0, v160, vcc
	v_cmp_eq_u32_e32 vcc, 6, v157
	v_cndmask_b32_e32 v102, 0, v160, vcc
	v_cmp_eq_u32_e32 vcc, 7, v157
	v_cndmask_b32_e32 v103, 0, v160, vcc
	s_waitcnt lgkmcnt(0)
	v_fma_f32 v97, -v30, v96, v97
	v_fma_f32 v98, -v34, v96, v98
	v_fma_f32 v99, -v38, v96, v99
	v_fma_f32 v100, -v42, v96, v100
	v_fma_f32 v101, -v50, v96, v101
	v_fma_f32 v102, -v58, v96, v102
	v_fma_f32 v103, -v66, v96, v103
	v_fma_f32 v98, -v35, v97, v98
	v_fma_f32 v99, -v39, v97, v99
	v_fma_f32 v100, -v43, v97, v100
	v_fma_f32 v101, -v51, v97, v101
	v_fma_f32 v102, -v59, v97, v102
	v_fma_f32 v103, -v67, v97, v103
	v_fma_f32 v99, -v40, v98, v99
	v_fma_f32 v100, -v44, v98, v100
	v_fma_f32 v101, -v52, v98, v101
	v_fma_f32 v102, -v60, v98, v102
	v_fma_f32 v103, -v68, v98, v103
	v_fma_f32 v100, -v45, v99, v100
	v_fma_f32 v101, -v53, v99, v101
	v_fma_f32 v102, -v61, v99, v102
	v_fma_f32 v103, -v69, v99, v103
	v_fma_f32 v101, -v54, v100, v101
	v_fma_f32 v102, -v62, v100, v102
	v_fma_f32 v103, -v70, v100, v103
	v_fma_f32 v102, -v63, v101, v102
	v_fma_f32 v103, -v71, v101, v103
	v_fma_f32 v103, -v72, v102, v103
	v_mul_f32_e32 v114, v74, v96
	v_mul_f32_e32 v115, v78, v96
	v_fmac_f32_e32 v115, v79, v97
	v_mul_f32_e32 v116, v82, v96
	v_fmac_f32_e32 v116, v83, v97
	v_fmac_f32_e32 v116, v84, v98
	v_mul_f32_e32 v117, v86, v96
	v_fmac_f32_e32 v117, v87, v97
	v_fmac_f32_e32 v117, v88, v98
	v_fmac_f32_e32 v117, v89, v99
	v_mul_f32_e32 v129, v216, v96
	v_fmac_f32_e32 v129, v217, v97
	v_fmac_f32_e32 v129, v218, v98
	v_fmac_f32_e32 v129, v219, v99
	v_fmac_f32_e32 v129, v220, v100
	v_mul_f32_e32 v130, v224, v96
	v_fmac_f32_e32 v130, v225, v97
	v_fmac_f32_e32 v130, v226, v98
	v_fmac_f32_e32 v130, v227, v99
	v_fmac_f32_e32 v130, v228, v100
	v_fmac_f32_e32 v130, v229, v101
	v_mul_f32_e32 v131, v140, v96
	v_fmac_f32_e32 v131, v141, v97
	v_fmac_f32_e32 v131, v142, v98
	v_fmac_f32_e32 v131, v143, v99
	v_fmac_f32_e32 v131, v144, v100
	v_fmac_f32_e32 v131, v145, v101
	v_fmac_f32_e32 v131, v146, v102
	v_mul_f32_e32 v153, v162, v96
	v_fmac_f32_e32 v153, v163, v97
	v_fmac_f32_e32 v153, v164, v98
	v_fmac_f32_e32 v153, v165, v99
	v_fmac_f32_e32 v153, v166, v100
	v_fmac_f32_e32 v153, v167, v101
	v_fmac_f32_e32 v153, v168, v102
	v_fmac_f32_e32 v153, v169, v103
	v_mul_f32_e32 v104, v104, v96
	v_mul_f32_e32 v105, v105, v97
	v_mul_f32_e32 v106, v106, v98
	v_mul_f32_e32 v107, v107, v99
	v_mul_f32_e32 v108, v108, v100
	v_mul_f32_e32 v109, v109, v101
	v_mul_f32_e32 v110, v110, v102
	v_mul_f32_e32 v111, v111, v103
	ds_write_b32 v137, v104 offset:0
	ds_write_b32 v137, v105 offset:32
	ds_write_b32 v137, v106 offset:64
	ds_write_b32 v137, v107 offset:96
	ds_write_b32 v137, v108 offset:128
	ds_write_b32 v137, v109 offset:160
	ds_write_b32 v137, v110 offset:192
	ds_write_b32 v137, v111 offset:224
	ds_write_b32 v137, v114 offset:256
	ds_write_b32 v137, v115 offset:288
	ds_write_b32 v137, v116 offset:320
	ds_write_b32 v137, v117 offset:352
	ds_write_b32 v137, v129 offset:384
	ds_write_b32 v137, v130 offset:416
	ds_write_b32 v137, v131 offset:448
	ds_write_b32 v137, v153 offset:480
	v_and_b32_e32 v153, 63, v180
	v_lshlrev_b32_e32 v138, 11, v152
	v_lshl_add_u32 v138, v153, 2, v138
	v_add_u32_e32 v138, 0x10800, v138
	v_lshlrev_b32_e32 v139, 5, v152
	v_add_u32_e32 v139, 0x21800, v139
	ds_read_b32 v30, v138 offset:0
	ds_read_b32 v31, v138 offset:256
	ds_read_b32 v32, v138 offset:512
	ds_read_b32 v33, v138 offset:768
	ds_read_b32 v34, v138 offset:1024
	ds_read_b32 v35, v138 offset:1280
	ds_read_b32 v36, v138 offset:1536
	ds_read_b32 v37, v138 offset:1792
	ds_read_b128 v[40:43], v139 offset:256
	ds_read_b128 v[44:47], v139 offset:272
	ds_read_b128 v[48:51], v139 offset:512
	ds_read_b128 v[52:55], v139 offset:528
	s_waitcnt lgkmcnt(0)
	v_mul_f32_e32 v30, v40, v30
	v_mul_f32_e32 v31, v41, v31
	v_mul_f32_e32 v32, v42, v32
	v_mul_f32_e32 v33, v43, v33
	v_mul_f32_e32 v34, v44, v34
	v_mul_f32_e32 v35, v45, v35
	v_mul_f32_e32 v36, v46, v36
	v_mul_f32_e32 v37, v47, v37
	v_mul_f32_e64 v48, -v40, v48
	v_mul_f32_e64 v49, -v41, v49
	v_mul_f32_e64 v50, -v42, v50
	v_mul_f32_e64 v51, -v43, v51
	v_mul_f32_e64 v52, -v44, v52
	v_mul_f32_e64 v53, -v45, v53
	v_mul_f32_e64 v54, -v46, v54
	v_mul_f32_e64 v55, -v47, v55
	ds_write_b32 v138, v30 offset:0
	ds_write_b32 v138, v31 offset:256
	ds_write_b32 v138, v32 offset:512
	ds_write_b32 v138, v33 offset:768
	ds_write_b32 v138, v34 offset:1024
	ds_write_b32 v138, v35 offset:1280
	ds_write_b32 v138, v36 offset:1536
	ds_write_b32 v138, v37 offset:1792
	ds_write_b128 v139, v[48:51]
	ds_write_b128 v139, v[52:55] offset:16
	s_lshl_b32 s0, s17, 6
	s_add_i32 s72, s0, s16
	v_and_b32_e32 v128, 63, v112
	s_cmp_eq_u32 s17, 31
	s_waitcnt lgkmcnt(0)
	s_barrier
	s_cbranch_scc1 .LBB0_549
	s_add_i32 s0, s72, 64
	s_mov_b32 s1, s73
	v_ashrrev_i32_e32 v27, 31, v26
	v_lshlrev_b32_e32 v2, 1, v23
	v_mov_b32_e32 v3, v94
	v_ashrrev_i32_e32 v23, 31, v22
	v_ashrrev_i32_e32 v25, 31, v24
	v_lshl_add_u64 v[18:19], s[0:1], 0, v[26:27]
	v_mov_b64_e32 v[20:21], s[12:13]
	v_lshl_add_u64 v[10:11], s[8:9], 0, v[2:3]
	v_lshl_add_u64 v[2:3], s[0:1], 0, v[22:23]
	v_lshl_add_u64 v[12:13], s[0:1], 0, v[24:25]
	v_mad_u64_u32 v[20:21], s[4:5], v18, s83, v[20:21]
	v_mad_u64_u32 v[6:7], s[4:5], v2, s83, v[10:11]
	v_mad_u64_u32 v[14:15], s[4:5], v12, s83, v[10:11]
	v_mad_i32_i24 v21, v19, s83, v21
	v_lshlrev_b32_e32 v18, 1, v28
	v_mov_b32_e32 v19, v94
	v_mad_i32_i24 v7, v3, s83, v7
	v_mad_i32_i24 v15, v13, s83, v15
	v_lshl_add_u64 v[18:19], v[20:21], 0, v[18:19]
	v_or_b32_e32 v22, s0, v128
	v_mov_b64_e32 v[20:21], s[14:15]
	global_load_dwordx4 v[2:5], v[6:7], off
	s_nop 0
	global_load_dwordx4 v[6:9], v[6:7], off offset:1024
	s_nop 0
	global_load_dwordx4 v[10:13], v[14:15], off
	s_nop 0
	global_load_dwordx4 v[14:17], v[14:15], off offset:1024
	v_mad_u64_u32 v[22:23], s[0:1], v22, s87, v[20:21]
	global_load_dwordx4 v[18:21], v[18:19], off offset:2048
	s_nop 0
	global_load_dword v126, v[22:23], off offset:512
	global_load_dword v127, v[22:23], off offset:528
.LBB0_549:
	v_readfirstlane_b32 s0, v180
	s_nop 1
	s_cmpk_ge_u32 s0, 0x100
	s_cbranch_scc1 .Lgdn_out
	v_and_b32_e32 v166, 15, v180
	v_bfe_u32 v167, v180, 4, 2
	v_lshrrev_b32_e32 v168, 6, v180
	v_lshrrev_b32_e32 v177, 2, v166
	v_and_b32_e32 v178, 1, v166
	v_lshl_add_u32 v177, v178, 2, v177
	v_lshlrev_b32_e32 v173, 5, v177
	v_mul_u32_u24_e32 v177, 0x210, v177
	v_and_b32_e32 v178, 2, v166
	v_lshl_add_u32 v173, v178, 7, v173
	v_lshl_add_u32 v173, v167, 2, v173
	v_add_u32_e32 v173, 0x14800, v173
	v_sub_u32_e32 v178, 2, v178
	v_mul_u32_u24_e32 v178, 0x4200, v178
	v_lshl_add_u32 v169, v167, 4, v177
	v_add_u32_e32 v169, v169, v178
	v_mul_u32_u24_e32 v177, 0x210, v167
	v_lshl_add_u32 v170, v166, 2, v177
	v_add_u32_e32 v170, 0x8400, v170
	v_lshlrev_b32_e32 v177, 6, v168
	v_lshl_add_u32 v177, v166, 2, v177
	v_lshl_add_u32 v177, v167, 8, v177
	v_add_u32_e32 v171, 0x10800, v177
	v_add_u32_e32 v172, 0x1d800, v177
	v_lshlrev_b32_e32 v177, 2, v167
	v_add_u32_e32 v174, 0x21800, v177
	v_add_u32_e32 v176, 0x21a00, v177
	v_mov_b32_e32 v175, 0x21900
	s_mov_b32 s40, 1
	s_mov_b32 s41, 0
	v_mov_b32_e32 v91, 0x15800
	v_mov_b32_e32 v92, 1
	v_mov_b32_e32 v108, 0
	v_mov_b32_e32 v109, 0
	ds_read_b128 v[22:25], v169 offset:0
	ds_read_b128 v[26:29], v169 offset:64
	ds_read_b128 v[30:33], v169 offset:128
	ds_read_b128 v[34:37], v169 offset:192
	ds_read_b128 v[38:41], v169 offset:256
	ds_read_b128 v[42:45], v169 offset:320
	ds_read_b128 v[46:49], v169 offset:384
	ds_read_b128 v[50:53], v169 offset:448
	s_waitcnt lgkmcnt(0)
	v_mfma_f32_16x16x4_f32 v[96:99], v22, v184, 0
	v_mfma_f32_16x16x4_f32 v[100:103], v23, v185, 0
	v_mfma_f32_16x16x4_f32 v[96:99], v24, v186, v[96:99]
	v_mfma_f32_16x16x4_f32 v[100:103], v25, v187, v[100:103]
	ds_read_b32 v54, v170 offset:0
	ds_read_b32 v55, v170 offset:64
	ds_read_b32 v56, v170 offset:128
	ds_read_b32 v57, v170 offset:192
	v_mfma_f32_16x16x4_f32 v[96:99], v26, v188, v[96:99]
	v_mfma_f32_16x16x4_f32 v[100:103], v27, v189, v[100:103]
	v_mfma_f32_16x16x4_f32 v[96:99], v28, v190, v[96:99]
	v_mfma_f32_16x16x4_f32 v[100:103], v29, v191, v[100:103]
	ds_read_b128 v[22:25], v169 offset:4224
	ds_read_b32 v58, v170 offset:256
	ds_read_b32 v59, v170 offset:320
	ds_read_b32 v60, v170 offset:384
	ds_read_b32 v61, v170 offset:448
	v_mfma_f32_16x16x4_f32 v[96:99], v30, v192, v[96:99]
	v_mfma_f32_16x16x4_f32 v[100:103], v31, v193, v[100:103]
	v_mfma_f32_16x16x4_f32 v[96:99], v32, v194, v[96:99]
	v_mfma_f32_16x16x4_f32 v[100:103], v33, v195, v[100:103]
	ds_read_b128 v[26:29], v169 offset:4288
	ds_read_b32 v62, v170 offset:2112
	ds_read_b32 v63, v170 offset:2176
	ds_read_b32 v64, v170 offset:2240
	ds_read_b32 v65, v170 offset:2304
	v_mfma_f32_16x16x4_f32 v[96:99], v34, v196, v[96:99]
	v_mfma_f32_16x16x4_f32 v[100:103], v35, v197, v[100:103]
	v_mfma_f32_16x16x4_f32 v[96:99], v36, v198, v[96:99]
	v_mfma_f32_16x16x4_f32 v[100:103], v37, v199, v[100:103]
	ds_read_b128 v[30:33], v169 offset:4352
	ds_read_b32 v66, v170 offset:2368
	ds_read_b32 v67, v170 offset:2432
	ds_read_b32 v68, v170 offset:2496
	ds_read_b32 v69, v170 offset:2560
	v_mfma_f32_16x16x4_f32 v[96:99], v38, v200, v[96:99]
	v_mfma_f32_16x16x4_f32 v[100:103], v39, v201, v[100:103]
	v_mfma_f32_16x16x4_f32 v[96:99], v40, v202, v[96:99]
	v_mfma_f32_16x16x4_f32 v[100:103], v41, v203, v[100:103]
	ds_read_b128 v[34:37], v169 offset:4416
	ds_read_b32 v95, v175 offset:284
	ds_read2_b32 v[72:73], v174 offset0:0 offset1:4
	ds_read2_b32 v[74:75], v176 offset0:0 offset1:4
	ds_read2st64_b32 v[70:71], v171 offset0:0 offset1:4
	ds_read_b32 v93, v173 offset:0
	ds_read_b32 v90, v173 offset:16
	v_mfma_f32_16x16x4_f32 v[96:99], v42, v204, v[96:99]
	v_mfma_f32_16x16x4_f32 v[100:103], v43, v205, v[100:103]
	v_mfma_f32_16x16x4_f32 v[96:99], v44, v206, v[96:99]
	v_mfma_f32_16x16x4_f32 v[100:103], v45, v207, v[100:103]
	ds_read_b128 v[38:41], v169 offset:4480
	v_mfma_f32_16x16x4_f32 v[96:99], v46, v208, v[96:99]
	v_mfma_f32_16x16x4_f32 v[100:103], v47, v209, v[100:103]
	v_mfma_f32_16x16x4_f32 v[96:99], v48, v210, v[96:99]
	v_mfma_f32_16x16x4_f32 v[100:103], v49, v211, v[100:103]
	ds_read_b128 v[42:45], v169 offset:4544
	v_mfma_f32_16x16x4_f32 v[96:99], v50, v212, v[96:99]
	v_mfma_f32_16x16x4_f32 v[100:103], v51, v213, v[100:103]
	v_mfma_f32_16x16x4_f32 v[96:99], v52, v214, v[96:99]
	v_mfma_f32_16x16x4_f32 v[100:103], v53, v215, v[100:103]
	ds_read_b128 v[46:49], v169 offset:4608
	ds_read_b128 v[50:53], v169 offset:4672
	s_waitcnt lgkmcnt(4)
	v_mul_f32_e32 v240, v238, v95
	v_pk_mul_f32 v[76:77], v[72:73], v[238:239] op_sel_hi:[1,0]
	v_pk_mul_f32 v[78:79], v[74:75], v[238:239] op_sel_hi:[1,0]
	v_rcp_f32_e32 v88, v240
	v_readfirstlane_b32 s0, v240
	s_nop 3
	v_pk_add_f32 v[96:97], v[96:97], v[100:101]
	v_pk_add_f32 v[98:99], v[98:99], v[102:103]
	v_pk_fma_f32 v[80:81], v[76:77], v[96:97], v[70:71]
	v_pk_mul_f32 v[110:111], v[78:79], v[98:99]
	s_nop 1
	v_mfma_f32_16x16x4_f32 v[82:85], v93, v80, v[108:111]
	v_mfma_f32_16x16x4_f32 v[82:85], v90, v81, v[82:85]
	s_cmp_lt_u32 s0, 0x2b800000
	s_cbranch_scc0 .Lgdn_nomat_0
	v_pk_mul_f32 v[184:185], v[184:185], v[240:241] op_sel_hi:[1,0]
	v_pk_mul_f32 v[186:187], v[186:187], v[240:241] op_sel_hi:[1,0]
	v_pk_mul_f32 v[188:189], v[188:189], v[240:241] op_sel_hi:[1,0]
	v_pk_mul_f32 v[190:191], v[190:191], v[240:241] op_sel_hi:[1,0]
	v_pk_mul_f32 v[192:193], v[192:193], v[240:241] op_sel_hi:[1,0]
	v_pk_mul_f32 v[194:195], v[194:195], v[240:241] op_sel_hi:[1,0]
	v_pk_mul_f32 v[196:197], v[196:197], v[240:241] op_sel_hi:[1,0]
	v_pk_mul_f32 v[198:199], v[198:199], v[240:241] op_sel_hi:[1,0]
	v_pk_mul_f32 v[200:201], v[200:201], v[240:241] op_sel_hi:[1,0]
	v_pk_mul_f32 v[202:203], v[202:203], v[240:241] op_sel_hi:[1,0]
	v_pk_mul_f32 v[204:205], v[204:205], v[240:241] op_sel_hi:[1,0]
	v_pk_mul_f32 v[206:207], v[206:207], v[240:241] op_sel_hi:[1,0]
	v_pk_mul_f32 v[208:209], v[208:209], v[240:241] op_sel_hi:[1,0]
	v_pk_mul_f32 v[210:211], v[210:211], v[240:241] op_sel_hi:[1,0]
	v_pk_mul_f32 v[212:213], v[212:213], v[240:241] op_sel_hi:[1,0]
	v_pk_mul_f32 v[214:215], v[214:215], v[240:241] op_sel_hi:[1,0]
	v_mov_b32_e32 v240, 1.0
	v_mov_b32_e32 v88, 1.0
.Lgdn_nomat_0:
	v_mov_b32_e32 v238, v240
	s_nop 7
	v_pk_mul_f32 v[86:87], v[82:83], v[88:89] op_sel_hi:[1,0]
	s_nop 1
	v_mfma_f32_16x16x4_f32 v[184:187], v54, v86, v[184:187]
	v_mfma_f32_16x16x4_f32 v[188:191], v55, v86, v[188:191]
	v_mfma_f32_16x16x4_f32 v[192:195], v56, v86, v[192:195]
	v_mfma_f32_16x16x4_f32 v[196:199], v57, v86, v[196:199]
	v_mfma_f32_16x16x4_f32 v[200:203], v58, v86, v[200:203]
	v_mfma_f32_16x16x4_f32 v[204:207], v59, v86, v[204:207]
	v_mfma_f32_16x16x4_f32 v[208:211], v60, v86, v[208:211]
	v_mfma_f32_16x16x4_f32 v[212:215], v61, v86, v[212:215]
	v_mfma_f32_16x16x4_f32 v[184:187], v62, v87, v[184:187]
	v_mfma_f32_16x16x4_f32 v[188:191], v63, v87, v[188:191]
	v_mfma_f32_16x16x4_f32 v[192:195], v64, v87, v[192:195]
	v_mfma_f32_16x16x4_f32 v[196:199], v65, v87, v[196:199]
	v_mfma_f32_16x16x4_f32 v[200:203], v66, v87, v[200:203]
	v_mfma_f32_16x16x4_f32 v[204:207], v67, v87, v[204:207]
	v_mfma_f32_16x16x4_f32 v[208:211], v68, v87, v[208:211]
	v_mfma_f32_16x16x4_f32 v[212:215], v69, v87, v[212:215]
	ds_write2st64_b32 v172, v84, v85 offset0:0 offset1:4
	s_mov_b64 exec, s[40:41]
	ds_add_u32 v91, v92 offset:0
	s_mov_b64 exec, -1
	s_waitcnt lgkmcnt(2)
	v_mfma_f32_16x16x4_f32 v[96:99], v22, v184, 0
	v_mfma_f32_16x16x4_f32 v[100:103], v23, v185, 0
	v_mfma_f32_16x16x4_f32 v[96:99], v24, v186, v[96:99]
	v_mfma_f32_16x16x4_f32 v[100:103], v25, v187, v[100:103]
	ds_read_b32 v54, v170 offset:4224
	ds_read_b32 v55, v170 offset:4288
	ds_read_b32 v56, v170 offset:4352
	ds_read_b32 v57, v170 offset:4416
	v_mfma_f32_16x16x4_f32 v[96:99], v26, v188, v[96:99]
	v_mfma_f32_16x16x4_f32 v[100:103], v27, v189, v[100:103]
	v_mfma_f32_16x16x4_f32 v[96:99], v28, v190, v[96:99]
	v_mfma_f32_16x16x4_f32 v[100:103], v29, v191, v[100:103]
	ds_read_b128 v[22:25], v169 offset:8448
	ds_read_b32 v58, v170 offset:4480
	ds_read_b32 v59, v170 offset:4544
	ds_read_b32 v60, v170 offset:4608
	ds_read_b32 v61, v170 offset:4672
	v_mfma_f32_16x16x4_f32 v[96:99], v30, v192, v[96:99]
	v_mfma_f32_16x16x4_f32 v[100:103], v31, v193, v[100:103]
	v_mfma_f32_16x16x4_f32 v[96:99], v32, v194, v[96:99]
	v_mfma_f32_16x16x4_f32 v[100:103], v33, v195, v[100:103]
	ds_read_b128 v[26:29], v169 offset:8512
	ds_read_b32 v62, v170 offset:6336
	ds_read_b32 v63, v170 offset:6400
	ds_read_b32 v64, v170 offset:6464
	ds_read_b32 v65, v170 offset:6528
	v_mfma_f32_16x16x4_f32 v[96:99], v34, v196, v[96:99]
	v_mfma_f32_16x16x4_f32 v[100:103], v35, v197, v[100:103]
	v_mfma_f32_16x16x4_f32 v[96:99], v36, v198, v[96:99]
	v_mfma_f32_16x16x4_f32 v[100:103], v37, v199, v[100:103]
	ds_read_b128 v[30:33], v169 offset:8576
	ds_read_b32 v66, v170 offset:6592
	ds_read_b32 v67, v170 offset:6656
	ds_read_b32 v68, v170 offset:6720
	ds_read_b32 v69, v170 offset:6784
	v_mfma_f32_16x16x4_f32 v[96:99], v38, v200, v[96:99]
	v_mfma_f32_16x16x4_f32 v[100:103], v39, v201, v[100:103]
	v_mfma_f32_16x16x4_f32 v[96:99], v40, v202, v[96:99]
	v_mfma_f32_16x16x4_f32 v[100:103], v41, v203, v[100:103]
	ds_read_b128 v[34:37], v169 offset:8640
	ds_read_b32 v95, v175 offset:316
	ds_read2_b32 v[72:73], v174 offset0:8 offset1:12
	ds_read2_b32 v[74:75], v176 offset0:8 offset1:12
	ds_read2st64_b32 v[70:71], v171 offset0:8 offset1:12
	ds_read_b32 v93, v173 offset:512
	ds_read_b32 v90, v173 offset:528
	v_mfma_f32_16x16x4_f32 v[96:99], v42, v204, v[96:99]
	v_mfma_f32_16x16x4_f32 v[100:103], v43, v205, v[100:103]
	v_mfma_f32_16x16x4_f32 v[96:99], v44, v206, v[96:99]
	v_mfma_f32_16x16x4_f32 v[100:103], v45, v207, v[100:103]
	ds_read_b128 v[38:41], v169 offset:8704
	v_mfma_f32_16x16x4_f32 v[96:99], v46, v208, v[96:99]
	v_mfma_f32_16x16x4_f32 v[100:103], v47, v209, v[100:103]
	v_mfma_f32_16x16x4_f32 v[96:99], v48, v210, v[96:99]
	v_mfma_f32_16x16x4_f32 v[100:103], v49, v211, v[100:103]
	ds_read_b128 v[42:45], v169 offset:8768
	v_mfma_f32_16x16x4_f32 v[96:99], v50, v212, v[96:99]
	v_mfma_f32_16x16x4_f32 v[100:103], v51, v213, v[100:103]
	v_mfma_f32_16x16x4_f32 v[96:99], v52, v214, v[96:99]
	v_mfma_f32_16x16x4_f32 v[100:103], v53, v215, v[100:103]
	ds_read_b128 v[46:49], v169 offset:8832
	ds_read_b128 v[50:53], v169 offset:8896
	s_waitcnt lgkmcnt(4)
	v_mul_f32_e32 v240, v238, v95
	v_pk_mul_f32 v[76:77], v[72:73], v[238:239] op_sel_hi:[1,0]
	v_pk_mul_f32 v[78:79], v[74:75], v[238:239] op_sel_hi:[1,0]
	v_rcp_f32_e32 v88, v240
	v_readfirstlane_b32 s0, v240
	s_nop 3
	v_pk_add_f32 v[96:97], v[96:97], v[100:101]
	v_pk_add_f32 v[98:99], v[98:99], v[102:103]
	v_pk_fma_f32 v[80:81], v[76:77], v[96:97], v[70:71]
	v_pk_mul_f32 v[110:111], v[78:79], v[98:99]
	s_nop 1
	v_mfma_f32_16x16x4_f32 v[82:85], v93, v80, v[108:111]
	v_mfma_f32_16x16x4_f32 v[82:85], v90, v81, v[82:85]
	s_cmp_lt_u32 s0, 0x2b800000
	s_cbranch_scc0 .Lgdn_nomat_1
	v_pk_mul_f32 v[184:185], v[184:185], v[240:241] op_sel_hi:[1,0]
	v_pk_mul_f32 v[186:187], v[186:187], v[240:241] op_sel_hi:[1,0]
	v_pk_mul_f32 v[188:189], v[188:189], v[240:241] op_sel_hi:[1,0]
	v_pk_mul_f32 v[190:191], v[190:191], v[240:241] op_sel_hi:[1,0]
	v_pk_mul_f32 v[192:193], v[192:193], v[240:241] op_sel_hi:[1,0]
	v_pk_mul_f32 v[194:195], v[194:195], v[240:241] op_sel_hi:[1,0]
	v_pk_mul_f32 v[196:197], v[196:197], v[240:241] op_sel_hi:[1,0]
	v_pk_mul_f32 v[198:199], v[198:199], v[240:241] op_sel_hi:[1,0]
	v_pk_mul_f32 v[200:201], v[200:201], v[240:241] op_sel_hi:[1,0]
	v_pk_mul_f32 v[202:203], v[202:203], v[240:241] op_sel_hi:[1,0]
	v_pk_mul_f32 v[204:205], v[204:205], v[240:241] op_sel_hi:[1,0]
	v_pk_mul_f32 v[206:207], v[206:207], v[240:241] op_sel_hi:[1,0]
	v_pk_mul_f32 v[208:209], v[208:209], v[240:241] op_sel_hi:[1,0]
	v_pk_mul_f32 v[210:211], v[210:211], v[240:241] op_sel_hi:[1,0]
	v_pk_mul_f32 v[212:213], v[212:213], v[240:241] op_sel_hi:[1,0]
	v_pk_mul_f32 v[214:215], v[214:215], v[240:241] op_sel_hi:[1,0]
	v_mov_b32_e32 v240, 1.0
	v_mov_b32_e32 v88, 1.0
.Lgdn_nomat_1:
	v_mov_b32_e32 v238, v240
	s_nop 7
	v_pk_mul_f32 v[86:87], v[82:83], v[88:89] op_sel_hi:[1,0]
	s_nop 1
	v_mfma_f32_16x16x4_f32 v[184:187], v54, v86, v[184:187]
	v_mfma_f32_16x16x4_f32 v[188:191], v55, v86, v[188:191]
	v_mfma_f32_16x16x4_f32 v[192:195], v56, v86, v[192:195]
	v_mfma_f32_16x16x4_f32 v[196:199], v57, v86, v[196:199]
	v_mfma_f32_16x16x4_f32 v[200:203], v58, v86, v[200:203]
	v_mfma_f32_16x16x4_f32 v[204:207], v59, v86, v[204:207]
	v_mfma_f32_16x16x4_f32 v[208:211], v60, v86, v[208:211]
	v_mfma_f32_16x16x4_f32 v[212:215], v61, v86, v[212:215]
	v_mfma_f32_16x16x4_f32 v[184:187], v62, v87, v[184:187]
	v_mfma_f32_16x16x4_f32 v[188:191], v63, v87, v[188:191]
	v_mfma_f32_16x16x4_f32 v[192:195], v64, v87, v[192:195]
	v_mfma_f32_16x16x4_f32 v[196:199], v65, v87, v[196:199]
	v_mfma_f32_16x16x4_f32 v[200:203], v66, v87, v[200:203]
	v_mfma_f32_16x16x4_f32 v[204:207], v67, v87, v[204:207]
	v_mfma_f32_16x16x4_f32 v[208:211], v68, v87, v[208:211]
	v_mfma_f32_16x16x4_f32 v[212:215], v69, v87, v[212:215]
	ds_write2st64_b32 v172, v84, v85 offset0:8 offset1:12
	s_mov_b64 exec, s[40:41]
	ds_add_u32 v91, v92 offset:4
	s_mov_b64 exec, -1
	s_waitcnt lgkmcnt(2)
	v_mfma_f32_16x16x4_f32 v[96:99], v22, v184, 0
	v_mfma_f32_16x16x4_f32 v[100:103], v23, v185, 0
	v_mfma_f32_16x16x4_f32 v[96:99], v24, v186, v[96:99]
	v_mfma_f32_16x16x4_f32 v[100:103], v25, v187, v[100:103]
	ds_read_b32 v54, v170 offset:8448
	ds_read_b32 v55, v170 offset:8512
	ds_read_b32 v56, v170 offset:8576
	ds_read_b32 v57, v170 offset:8640
	v_mfma_f32_16x16x4_f32 v[96:99], v26, v188, v[96:99]
	v_mfma_f32_16x16x4_f32 v[100:103], v27, v189, v[100:103]
	v_mfma_f32_16x16x4_f32 v[96:99], v28, v190, v[96:99]
	v_mfma_f32_16x16x4_f32 v[100:103], v29, v191, v[100:103]
	ds_read_b128 v[22:25], v169 offset:12672
	ds_read_b32 v58, v170 offset:8704
	ds_read_b32 v59, v170 offset:8768
	ds_read_b32 v60, v170 offset:8832
	ds_read_b32 v61, v170 offset:8896
	v_mfma_f32_16x16x4_f32 v[96:99], v30, v192, v[96:99]
	v_mfma_f32_16x16x4_f32 v[100:103], v31, v193, v[100:103]
	v_mfma_f32_16x16x4_f32 v[96:99], v32, v194, v[96:99]
	v_mfma_f32_16x16x4_f32 v[100:103], v33, v195, v[100:103]
	ds_read_b128 v[26:29], v169 offset:12736
	ds_read_b32 v62, v170 offset:10560
	ds_read_b32 v63, v170 offset:10624
	ds_read_b32 v64, v170 offset:10688
	ds_read_b32 v65, v170 offset:10752
	v_mfma_f32_16x16x4_f32 v[96:99], v34, v196, v[96:99]
	v_mfma_f32_16x16x4_f32 v[100:103], v35, v197, v[100:103]
	v_mfma_f32_16x16x4_f32 v[96:99], v36, v198, v[96:99]
	v_mfma_f32_16x16x4_f32 v[100:103], v37, v199, v[100:103]
	ds_read_b128 v[30:33], v169 offset:12800
	ds_read_b32 v66, v170 offset:10816
	ds_read_b32 v67, v170 offset:10880
	ds_read_b32 v68, v170 offset:10944
	ds_read_b32 v69, v170 offset:11008
	v_mfma_f32_16x16x4_f32 v[96:99], v38, v200, v[96:99]
	v_mfma_f32_16x16x4_f32 v[100:103], v39, v201, v[100:103]
	v_mfma_f32_16x16x4_f32 v[96:99], v40, v202, v[96:99]
	v_mfma_f32_16x16x4_f32 v[100:103], v41, v203, v[100:103]
	ds_read_b128 v[34:37], v169 offset:12864
	ds_read_b32 v95, v175 offset:348
	ds_read2_b32 v[72:73], v174 offset0:16 offset1:20
	ds_read2_b32 v[74:75], v176 offset0:16 offset1:20
	ds_read2st64_b32 v[70:71], v171 offset0:16 offset1:20
	ds_read_b32 v93, v173 offset:1024
	ds_read_b32 v90, v173 offset:1040
	v_mfma_f32_16x16x4_f32 v[96:99], v42, v204, v[96:99]
	v_mfma_f32_16x16x4_f32 v[100:103], v43, v205, v[100:103]
	v_mfma_f32_16x16x4_f32 v[96:99], v44, v206, v[96:99]
	v_mfma_f32_16x16x4_f32 v[100:103], v45, v207, v[100:103]
	ds_read_b128 v[38:41], v169 offset:12928
	v_mfma_f32_16x16x4_f32 v[96:99], v46, v208, v[96:99]
	v_mfma_f32_16x16x4_f32 v[100:103], v47, v209, v[100:103]
	v_mfma_f32_16x16x4_f32 v[96:99], v48, v210, v[96:99]
	v_mfma_f32_16x16x4_f32 v[100:103], v49, v211, v[100:103]
	ds_read_b128 v[42:45], v169 offset:12992
	v_mfma_f32_16x16x4_f32 v[96:99], v50, v212, v[96:99]
	v_mfma_f32_16x16x4_f32 v[100:103], v51, v213, v[100:103]
	v_mfma_f32_16x16x4_f32 v[96:99], v52, v214, v[96:99]
	v_mfma_f32_16x16x4_f32 v[100:103], v53, v215, v[100:103]
	ds_read_b128 v[46:49], v169 offset:13056
	ds_read_b128 v[50:53], v169 offset:13120
	s_waitcnt lgkmcnt(4)
	v_mul_f32_e32 v240, v238, v95
	v_pk_mul_f32 v[76:77], v[72:73], v[238:239] op_sel_hi:[1,0]
	v_pk_mul_f32 v[78:79], v[74:75], v[238:239] op_sel_hi:[1,0]
	v_rcp_f32_e32 v88, v240
	v_readfirstlane_b32 s0, v240
	s_nop 3
	v_pk_add_f32 v[96:97], v[96:97], v[100:101]
	v_pk_add_f32 v[98:99], v[98:99], v[102:103]
	v_pk_fma_f32 v[80:81], v[76:77], v[96:97], v[70:71]
	v_pk_mul_f32 v[110:111], v[78:79], v[98:99]
	s_nop 1
	v_mfma_f32_16x16x4_f32 v[82:85], v93, v80, v[108:111]
	v_mfma_f32_16x16x4_f32 v[82:85], v90, v81, v[82:85]
	s_cmp_lt_u32 s0, 0x2b800000
	s_cbranch_scc0 .Lgdn_nomat_2
	v_pk_mul_f32 v[184:185], v[184:185], v[240:241] op_sel_hi:[1,0]
	v_pk_mul_f32 v[186:187], v[186:187], v[240:241] op_sel_hi:[1,0]
	v_pk_mul_f32 v[188:189], v[188:189], v[240:241] op_sel_hi:[1,0]
	v_pk_mul_f32 v[190:191], v[190:191], v[240:241] op_sel_hi:[1,0]
	v_pk_mul_f32 v[192:193], v[192:193], v[240:241] op_sel_hi:[1,0]
	v_pk_mul_f32 v[194:195], v[194:195], v[240:241] op_sel_hi:[1,0]
	v_pk_mul_f32 v[196:197], v[196:197], v[240:241] op_sel_hi:[1,0]
	v_pk_mul_f32 v[198:199], v[198:199], v[240:241] op_sel_hi:[1,0]
	v_pk_mul_f32 v[200:201], v[200:201], v[240:241] op_sel_hi:[1,0]
	v_pk_mul_f32 v[202:203], v[202:203], v[240:241] op_sel_hi:[1,0]
	v_pk_mul_f32 v[204:205], v[204:205], v[240:241] op_sel_hi:[1,0]
	v_pk_mul_f32 v[206:207], v[206:207], v[240:241] op_sel_hi:[1,0]
	v_pk_mul_f32 v[208:209], v[208:209], v[240:241] op_sel_hi:[1,0]
	v_pk_mul_f32 v[210:211], v[210:211], v[240:241] op_sel_hi:[1,0]
	v_pk_mul_f32 v[212:213], v[212:213], v[240:241] op_sel_hi:[1,0]
	v_pk_mul_f32 v[214:215], v[214:215], v[240:241] op_sel_hi:[1,0]
	v_mov_b32_e32 v240, 1.0
	v_mov_b32_e32 v88, 1.0
.Lgdn_nomat_2:
	v_mov_b32_e32 v238, v240
	s_nop 7
	v_pk_mul_f32 v[86:87], v[82:83], v[88:89] op_sel_hi:[1,0]
	s_nop 1
	v_mfma_f32_16x16x4_f32 v[184:187], v54, v86, v[184:187]
	v_mfma_f32_16x16x4_f32 v[188:191], v55, v86, v[188:191]
	v_mfma_f32_16x16x4_f32 v[192:195], v56, v86, v[192:195]
	v_mfma_f32_16x16x4_f32 v[196:199], v57, v86, v[196:199]
	v_mfma_f32_16x16x4_f32 v[200:203], v58, v86, v[200:203]
	v_mfma_f32_16x16x4_f32 v[204:207], v59, v86, v[204:207]
	v_mfma_f32_16x16x4_f32 v[208:211], v60, v86, v[208:211]
	v_mfma_f32_16x16x4_f32 v[212:215], v61, v86, v[212:215]
	v_mfma_f32_16x16x4_f32 v[184:187], v62, v87, v[184:187]
	v_mfma_f32_16x16x4_f32 v[188:191], v63, v87, v[188:191]
	v_mfma_f32_16x16x4_f32 v[192:195], v64, v87, v[192:195]
	v_mfma_f32_16x16x4_f32 v[196:199], v65, v87, v[196:199]
	v_mfma_f32_16x16x4_f32 v[200:203], v66, v87, v[200:203]
	v_mfma_f32_16x16x4_f32 v[204:207], v67, v87, v[204:207]
	v_mfma_f32_16x16x4_f32 v[208:211], v68, v87, v[208:211]
	v_mfma_f32_16x16x4_f32 v[212:215], v69, v87, v[212:215]
	ds_write2st64_b32 v172, v84, v85 offset0:16 offset1:20
	s_mov_b64 exec, s[40:41]
	ds_add_u32 v91, v92 offset:8
	s_mov_b64 exec, -1
	s_waitcnt lgkmcnt(2)
	v_mfma_f32_16x16x4_f32 v[96:99], v22, v184, 0
	v_mfma_f32_16x16x4_f32 v[100:103], v23, v185, 0
	v_mfma_f32_16x16x4_f32 v[96:99], v24, v186, v[96:99]
	v_mfma_f32_16x16x4_f32 v[100:103], v25, v187, v[100:103]
	ds_read_b32 v54, v170 offset:12672
	ds_read_b32 v55, v170 offset:12736
	ds_read_b32 v56, v170 offset:12800
	ds_read_b32 v57, v170 offset:12864
	v_mfma_f32_16x16x4_f32 v[96:99], v26, v188, v[96:99]
	v_mfma_f32_16x16x4_f32 v[100:103], v27, v189, v[100:103]
	v_mfma_f32_16x16x4_f32 v[96:99], v28, v190, v[96:99]
	v_mfma_f32_16x16x4_f32 v[100:103], v29, v191, v[100:103]
	ds_read_b128 v[22:25], v169 offset:16896
	ds_read_b32 v58, v170 offset:12928
	ds_read_b32 v59, v170 offset:12992
	ds_read_b32 v60, v170 offset:13056
	ds_read_b32 v61, v170 offset:13120
	v_mfma_f32_16x16x4_f32 v[96:99], v30, v192, v[96:99]
	v_mfma_f32_16x16x4_f32 v[100:103], v31, v193, v[100:103]
	v_mfma_f32_16x16x4_f32 v[96:99], v32, v194, v[96:99]
	v_mfma_f32_16x16x4_f32 v[100:103], v33, v195, v[100:103]
	ds_read_b128 v[26:29], v169 offset:16960
	ds_read_b32 v62, v170 offset:14784
	ds_read_b32 v63, v170 offset:14848
	ds_read_b32 v64, v170 offset:14912
	ds_read_b32 v65, v170 offset:14976
	v_mfma_f32_16x16x4_f32 v[96:99], v34, v196, v[96:99]
	v_mfma_f32_16x16x4_f32 v[100:103], v35, v197, v[100:103]
	v_mfma_f32_16x16x4_f32 v[96:99], v36, v198, v[96:99]
	v_mfma_f32_16x16x4_f32 v[100:103], v37, v199, v[100:103]
	ds_read_b128 v[30:33], v169 offset:17024
	ds_read_b32 v66, v170 offset:15040
	ds_read_b32 v67, v170 offset:15104
	ds_read_b32 v68, v170 offset:15168
	ds_read_b32 v69, v170 offset:15232
	v_mfma_f32_16x16x4_f32 v[96:99], v38, v200, v[96:99]
	v_mfma_f32_16x16x4_f32 v[100:103], v39, v201, v[100:103]
	v_mfma_f32_16x16x4_f32 v[96:99], v40, v202, v[96:99]
	v_mfma_f32_16x16x4_f32 v[100:103], v41, v203, v[100:103]
	ds_read_b128 v[34:37], v169 offset:17088
	ds_read_b32 v95, v175 offset:380
	ds_read2_b32 v[72:73], v174 offset0:24 offset1:28
	ds_read2_b32 v[74:75], v176 offset0:24 offset1:28
	ds_read2st64_b32 v[70:71], v171 offset0:24 offset1:28
	ds_read_b32 v93, v173 offset:1536
	ds_read_b32 v90, v173 offset:1552
	v_mfma_f32_16x16x4_f32 v[96:99], v42, v204, v[96:99]
	v_mfma_f32_16x16x4_f32 v[100:103], v43, v205, v[100:103]
	v_mfma_f32_16x16x4_f32 v[96:99], v44, v206, v[96:99]
	v_mfma_f32_16x16x4_f32 v[100:103], v45, v207, v[100:103]
	ds_read_b128 v[38:41], v169 offset:17152
	v_mfma_f32_16x16x4_f32 v[96:99], v46, v208, v[96:99]
	v_mfma_f32_16x16x4_f32 v[100:103], v47, v209, v[100:103]
	v_mfma_f32_16x16x4_f32 v[96:99], v48, v210, v[96:99]
	v_mfma_f32_16x16x4_f32 v[100:103], v49, v211, v[100:103]
	ds_read_b128 v[42:45], v169 offset:17216
	v_mfma_f32_16x16x4_f32 v[96:99], v50, v212, v[96:99]
	v_mfma_f32_16x16x4_f32 v[100:103], v51, v213, v[100:103]
	v_mfma_f32_16x16x4_f32 v[96:99], v52, v214, v[96:99]
	v_mfma_f32_16x16x4_f32 v[100:103], v53, v215, v[100:103]
	ds_read_b128 v[46:49], v169 offset:17280
	ds_read_b128 v[50:53], v169 offset:17344
	s_waitcnt lgkmcnt(4)
	v_mul_f32_e32 v240, v238, v95
	v_pk_mul_f32 v[76:77], v[72:73], v[238:239] op_sel_hi:[1,0]
	v_pk_mul_f32 v[78:79], v[74:75], v[238:239] op_sel_hi:[1,0]
	v_rcp_f32_e32 v88, v240
	v_readfirstlane_b32 s0, v240
	s_nop 3
	v_pk_add_f32 v[96:97], v[96:97], v[100:101]
	v_pk_add_f32 v[98:99], v[98:99], v[102:103]
	v_pk_fma_f32 v[80:81], v[76:77], v[96:97], v[70:71]
	v_pk_mul_f32 v[110:111], v[78:79], v[98:99]
	s_nop 1
	v_mfma_f32_16x16x4_f32 v[82:85], v93, v80, v[108:111]
	v_mfma_f32_16x16x4_f32 v[82:85], v90, v81, v[82:85]
	s_cmp_lt_u32 s0, 0x2b800000
	s_cbranch_scc0 .Lgdn_nomat_3
	v_pk_mul_f32 v[184:185], v[184:185], v[240:241] op_sel_hi:[1,0]
	v_pk_mul_f32 v[186:187], v[186:187], v[240:241] op_sel_hi:[1,0]
	v_pk_mul_f32 v[188:189], v[188:189], v[240:241] op_sel_hi:[1,0]
	v_pk_mul_f32 v[190:191], v[190:191], v[240:241] op_sel_hi:[1,0]
	v_pk_mul_f32 v[192:193], v[192:193], v[240:241] op_sel_hi:[1,0]
	v_pk_mul_f32 v[194:195], v[194:195], v[240:241] op_sel_hi:[1,0]
	v_pk_mul_f32 v[196:197], v[196:197], v[240:241] op_sel_hi:[1,0]
	v_pk_mul_f32 v[198:199], v[198:199], v[240:241] op_sel_hi:[1,0]
	v_pk_mul_f32 v[200:201], v[200:201], v[240:241] op_sel_hi:[1,0]
	v_pk_mul_f32 v[202:203], v[202:203], v[240:241] op_sel_hi:[1,0]
	v_pk_mul_f32 v[204:205], v[204:205], v[240:241] op_sel_hi:[1,0]
	v_pk_mul_f32 v[206:207], v[206:207], v[240:241] op_sel_hi:[1,0]
	v_pk_mul_f32 v[208:209], v[208:209], v[240:241] op_sel_hi:[1,0]
	v_pk_mul_f32 v[210:211], v[210:211], v[240:241] op_sel_hi:[1,0]
	v_pk_mul_f32 v[212:213], v[212:213], v[240:241] op_sel_hi:[1,0]
	v_pk_mul_f32 v[214:215], v[214:215], v[240:241] op_sel_hi:[1,0]
	v_mov_b32_e32 v240, 1.0
	v_mov_b32_e32 v88, 1.0
.Lgdn_nomat_3:
	v_mov_b32_e32 v238, v240
	s_nop 7
	v_pk_mul_f32 v[86:87], v[82:83], v[88:89] op_sel_hi:[1,0]
	s_nop 1
	v_mfma_f32_16x16x4_f32 v[184:187], v54, v86, v[184:187]
	v_mfma_f32_16x16x4_f32 v[188:191], v55, v86, v[188:191]
	v_mfma_f32_16x16x4_f32 v[192:195], v56, v86, v[192:195]
	v_mfma_f32_16x16x4_f32 v[196:199], v57, v86, v[196:199]
	v_mfma_f32_16x16x4_f32 v[200:203], v58, v86, v[200:203]
	v_mfma_f32_16x16x4_f32 v[204:207], v59, v86, v[204:207]
	v_mfma_f32_16x16x4_f32 v[208:211], v60, v86, v[208:211]
	v_mfma_f32_16x16x4_f32 v[212:215], v61, v86, v[212:215]
	v_mfma_f32_16x16x4_f32 v[184:187], v62, v87, v[184:187]
	v_mfma_f32_16x16x4_f32 v[188:191], v63, v87, v[188:191]
	v_mfma_f32_16x16x4_f32 v[192:195], v64, v87, v[192:195]
	v_mfma_f32_16x16x4_f32 v[196:199], v65, v87, v[196:199]
	v_mfma_f32_16x16x4_f32 v[200:203], v66, v87, v[200:203]
	v_mfma_f32_16x16x4_f32 v[204:207], v67, v87, v[204:207]
	v_mfma_f32_16x16x4_f32 v[208:211], v68, v87, v[208:211]
	v_mfma_f32_16x16x4_f32 v[212:215], v69, v87, v[212:215]
	ds_write2st64_b32 v172, v84, v85 offset0:24 offset1:28
	s_mov_b64 exec, s[40:41]
	ds_add_u32 v91, v92 offset:12
	s_mov_b64 exec, -1
	s_waitcnt lgkmcnt(2)
	v_mfma_f32_16x16x4_f32 v[96:99], v22, v184, 0
	v_mfma_f32_16x16x4_f32 v[100:103], v23, v185, 0
	v_mfma_f32_16x16x4_f32 v[96:99], v24, v186, v[96:99]
	v_mfma_f32_16x16x4_f32 v[100:103], v25, v187, v[100:103]
	ds_read_b32 v54, v170 offset:16896
	ds_read_b32 v55, v170 offset:16960
	ds_read_b32 v56, v170 offset:17024
	ds_read_b32 v57, v170 offset:17088
	v_mfma_f32_16x16x4_f32 v[96:99], v26, v188, v[96:99]
	v_mfma_f32_16x16x4_f32 v[100:103], v27, v189, v[100:103]
	v_mfma_f32_16x16x4_f32 v[96:99], v28, v190, v[96:99]
	v_mfma_f32_16x16x4_f32 v[100:103], v29, v191, v[100:103]
	ds_read_b128 v[22:25], v169 offset:21120
	ds_read_b32 v58, v170 offset:17152
	ds_read_b32 v59, v170 offset:17216
	ds_read_b32 v60, v170 offset:17280
	ds_read_b32 v61, v170 offset:17344
	v_mfma_f32_16x16x4_f32 v[96:99], v30, v192, v[96:99]
	v_mfma_f32_16x16x4_f32 v[100:103], v31, v193, v[100:103]
	v_mfma_f32_16x16x4_f32 v[96:99], v32, v194, v[96:99]
	v_mfma_f32_16x16x4_f32 v[100:103], v33, v195, v[100:103]
	ds_read_b128 v[26:29], v169 offset:21184
	ds_read_b32 v62, v170 offset:19008
	ds_read_b32 v63, v170 offset:19072
	ds_read_b32 v64, v170 offset:19136
	ds_read_b32 v65, v170 offset:19200
	v_mfma_f32_16x16x4_f32 v[96:99], v34, v196, v[96:99]
	v_mfma_f32_16x16x4_f32 v[100:103], v35, v197, v[100:103]
	v_mfma_f32_16x16x4_f32 v[96:99], v36, v198, v[96:99]
	v_mfma_f32_16x16x4_f32 v[100:103], v37, v199, v[100:103]
	ds_read_b128 v[30:33], v169 offset:21248
	ds_read_b32 v66, v170 offset:19264
	ds_read_b32 v67, v170 offset:19328
	ds_read_b32 v68, v170 offset:19392
	ds_read_b32 v69, v170 offset:19456
	v_mfma_f32_16x16x4_f32 v[96:99], v38, v200, v[96:99]
	v_mfma_f32_16x16x4_f32 v[100:103], v39, v201, v[100:103]
	v_mfma_f32_16x16x4_f32 v[96:99], v40, v202, v[96:99]
	v_mfma_f32_16x16x4_f32 v[100:103], v41, v203, v[100:103]
	ds_read_b128 v[34:37], v169 offset:21312
	ds_read_b32 v95, v175 offset:412
	ds_read2_b32 v[72:73], v174 offset0:32 offset1:36
	ds_read2_b32 v[74:75], v176 offset0:32 offset1:36
	ds_read2st64_b32 v[70:71], v171 offset0:32 offset1:36
	ds_read_b32 v93, v173 offset:2048
	ds_read_b32 v90, v173 offset:2064
	v_mfma_f32_16x16x4_f32 v[96:99], v42, v204, v[96:99]
	v_mfma_f32_16x16x4_f32 v[100:103], v43, v205, v[100:103]
	v_mfma_f32_16x16x4_f32 v[96:99], v44, v206, v[96:99]
	v_mfma_f32_16x16x4_f32 v[100:103], v45, v207, v[100:103]
	ds_read_b128 v[38:41], v169 offset:21376
	v_mfma_f32_16x16x4_f32 v[96:99], v46, v208, v[96:99]
	v_mfma_f32_16x16x4_f32 v[100:103], v47, v209, v[100:103]
	v_mfma_f32_16x16x4_f32 v[96:99], v48, v210, v[96:99]
	v_mfma_f32_16x16x4_f32 v[100:103], v49, v211, v[100:103]
	ds_read_b128 v[42:45], v169 offset:21440
	v_mfma_f32_16x16x4_f32 v[96:99], v50, v212, v[96:99]
	v_mfma_f32_16x16x4_f32 v[100:103], v51, v213, v[100:103]
	v_mfma_f32_16x16x4_f32 v[96:99], v52, v214, v[96:99]
	v_mfma_f32_16x16x4_f32 v[100:103], v53, v215, v[100:103]
	ds_read_b128 v[46:49], v169 offset:21504
	ds_read_b128 v[50:53], v169 offset:21568
	s_waitcnt lgkmcnt(4)
	v_mul_f32_e32 v240, v238, v95
	v_pk_mul_f32 v[76:77], v[72:73], v[238:239] op_sel_hi:[1,0]
	v_pk_mul_f32 v[78:79], v[74:75], v[238:239] op_sel_hi:[1,0]
	v_rcp_f32_e32 v88, v240
	v_readfirstlane_b32 s0, v240
	s_nop 3
	v_pk_add_f32 v[96:97], v[96:97], v[100:101]
	v_pk_add_f32 v[98:99], v[98:99], v[102:103]
	v_pk_fma_f32 v[80:81], v[76:77], v[96:97], v[70:71]
	v_pk_mul_f32 v[110:111], v[78:79], v[98:99]
	s_nop 1
	v_mfma_f32_16x16x4_f32 v[82:85], v93, v80, v[108:111]
	v_mfma_f32_16x16x4_f32 v[82:85], v90, v81, v[82:85]
	s_cmp_lt_u32 s0, 0x2b800000
	s_cbranch_scc0 .Lgdn_nomat_4
	v_pk_mul_f32 v[184:185], v[184:185], v[240:241] op_sel_hi:[1,0]
	v_pk_mul_f32 v[186:187], v[186:187], v[240:241] op_sel_hi:[1,0]
	v_pk_mul_f32 v[188:189], v[188:189], v[240:241] op_sel_hi:[1,0]
	v_pk_mul_f32 v[190:191], v[190:191], v[240:241] op_sel_hi:[1,0]
	v_pk_mul_f32 v[192:193], v[192:193], v[240:241] op_sel_hi:[1,0]
	v_pk_mul_f32 v[194:195], v[194:195], v[240:241] op_sel_hi:[1,0]
	v_pk_mul_f32 v[196:197], v[196:197], v[240:241] op_sel_hi:[1,0]
	v_pk_mul_f32 v[198:199], v[198:199], v[240:241] op_sel_hi:[1,0]
	v_pk_mul_f32 v[200:201], v[200:201], v[240:241] op_sel_hi:[1,0]
	v_pk_mul_f32 v[202:203], v[202:203], v[240:241] op_sel_hi:[1,0]
	v_pk_mul_f32 v[204:205], v[204:205], v[240:241] op_sel_hi:[1,0]
	v_pk_mul_f32 v[206:207], v[206:207], v[240:241] op_sel_hi:[1,0]
	v_pk_mul_f32 v[208:209], v[208:209], v[240:241] op_sel_hi:[1,0]
	v_pk_mul_f32 v[210:211], v[210:211], v[240:241] op_sel_hi:[1,0]
	v_pk_mul_f32 v[212:213], v[212:213], v[240:241] op_sel_hi:[1,0]
	v_pk_mul_f32 v[214:215], v[214:215], v[240:241] op_sel_hi:[1,0]
	v_mov_b32_e32 v240, 1.0
	v_mov_b32_e32 v88, 1.0
.Lgdn_nomat_4:
	v_mov_b32_e32 v238, v240
	s_nop 7
	v_pk_mul_f32 v[86:87], v[82:83], v[88:89] op_sel_hi:[1,0]
	s_nop 1
	v_mfma_f32_16x16x4_f32 v[184:187], v54, v86, v[184:187]
	v_mfma_f32_16x16x4_f32 v[188:191], v55, v86, v[188:191]
	v_mfma_f32_16x16x4_f32 v[192:195], v56, v86, v[192:195]
	v_mfma_f32_16x16x4_f32 v[196:199], v57, v86, v[196:199]
	v_mfma_f32_16x16x4_f32 v[200:203], v58, v86, v[200:203]
	v_mfma_f32_16x16x4_f32 v[204:207], v59, v86, v[204:207]
	v_mfma_f32_16x16x4_f32 v[208:211], v60, v86, v[208:211]
	v_mfma_f32_16x16x4_f32 v[212:215], v61, v86, v[212:215]
	v_mfma_f32_16x16x4_f32 v[184:187], v62, v87, v[184:187]
	v_mfma_f32_16x16x4_f32 v[188:191], v63, v87, v[188:191]
	v_mfma_f32_16x16x4_f32 v[192:195], v64, v87, v[192:195]
	v_mfma_f32_16x16x4_f32 v[196:199], v65, v87, v[196:199]
	v_mfma_f32_16x16x4_f32 v[200:203], v66, v87, v[200:203]
	v_mfma_f32_16x16x4_f32 v[204:207], v67, v87, v[204:207]
	v_mfma_f32_16x16x4_f32 v[208:211], v68, v87, v[208:211]
	v_mfma_f32_16x16x4_f32 v[212:215], v69, v87, v[212:215]
	ds_write2st64_b32 v172, v84, v85 offset0:32 offset1:36
	s_mov_b64 exec, s[40:41]
	ds_add_u32 v91, v92 offset:16
	s_mov_b64 exec, -1
	s_waitcnt lgkmcnt(2)
	v_mfma_f32_16x16x4_f32 v[96:99], v22, v184, 0
	v_mfma_f32_16x16x4_f32 v[100:103], v23, v185, 0
	v_mfma_f32_16x16x4_f32 v[96:99], v24, v186, v[96:99]
	v_mfma_f32_16x16x4_f32 v[100:103], v25, v187, v[100:103]
	ds_read_b32 v54, v170 offset:21120
	ds_read_b32 v55, v170 offset:21184
	ds_read_b32 v56, v170 offset:21248
	ds_read_b32 v57, v170 offset:21312
	v_mfma_f32_16x16x4_f32 v[96:99], v26, v188, v[96:99]
	v_mfma_f32_16x16x4_f32 v[100:103], v27, v189, v[100:103]
	v_mfma_f32_16x16x4_f32 v[96:99], v28, v190, v[96:99]
	v_mfma_f32_16x16x4_f32 v[100:103], v29, v191, v[100:103]
	ds_read_b128 v[22:25], v169 offset:25344
	ds_read_b32 v58, v170 offset:21376
	ds_read_b32 v59, v170 offset:21440
	ds_read_b32 v60, v170 offset:21504
	ds_read_b32 v61, v170 offset:21568
	v_mfma_f32_16x16x4_f32 v[96:99], v30, v192, v[96:99]
	v_mfma_f32_16x16x4_f32 v[100:103], v31, v193, v[100:103]
	v_mfma_f32_16x16x4_f32 v[96:99], v32, v194, v[96:99]
	v_mfma_f32_16x16x4_f32 v[100:103], v33, v195, v[100:103]
	ds_read_b128 v[26:29], v169 offset:25408
	ds_read_b32 v62, v170 offset:23232
	ds_read_b32 v63, v170 offset:23296
	ds_read_b32 v64, v170 offset:23360
	ds_read_b32 v65, v170 offset:23424
	v_mfma_f32_16x16x4_f32 v[96:99], v34, v196, v[96:99]
	v_mfma_f32_16x16x4_f32 v[100:103], v35, v197, v[100:103]
	v_mfma_f32_16x16x4_f32 v[96:99], v36, v198, v[96:99]
	v_mfma_f32_16x16x4_f32 v[100:103], v37, v199, v[100:103]
	ds_read_b128 v[30:33], v169 offset:25472
	ds_read_b32 v66, v170 offset:23488
	ds_read_b32 v67, v170 offset:23552
	ds_read_b32 v68, v170 offset:23616
	ds_read_b32 v69, v170 offset:23680
	v_mfma_f32_16x16x4_f32 v[96:99], v38, v200, v[96:99]
	v_mfma_f32_16x16x4_f32 v[100:103], v39, v201, v[100:103]
	v_mfma_f32_16x16x4_f32 v[96:99], v40, v202, v[96:99]
	v_mfma_f32_16x16x4_f32 v[100:103], v41, v203, v[100:103]
	ds_read_b128 v[34:37], v169 offset:25536
	ds_read_b32 v95, v175 offset:444
	ds_read2_b32 v[72:73], v174 offset0:40 offset1:44
	ds_read2_b32 v[74:75], v176 offset0:40 offset1:44
	ds_read2st64_b32 v[70:71], v171 offset0:40 offset1:44
	ds_read_b32 v93, v173 offset:2560
	ds_read_b32 v90, v173 offset:2576
	v_mfma_f32_16x16x4_f32 v[96:99], v42, v204, v[96:99]
	v_mfma_f32_16x16x4_f32 v[100:103], v43, v205, v[100:103]
	v_mfma_f32_16x16x4_f32 v[96:99], v44, v206, v[96:99]
	v_mfma_f32_16x16x4_f32 v[100:103], v45, v207, v[100:103]
	ds_read_b128 v[38:41], v169 offset:25600
	v_mfma_f32_16x16x4_f32 v[96:99], v46, v208, v[96:99]
	v_mfma_f32_16x16x4_f32 v[100:103], v47, v209, v[100:103]
	v_mfma_f32_16x16x4_f32 v[96:99], v48, v210, v[96:99]
	v_mfma_f32_16x16x4_f32 v[100:103], v49, v211, v[100:103]
	ds_read_b128 v[42:45], v169 offset:25664
	v_mfma_f32_16x16x4_f32 v[96:99], v50, v212, v[96:99]
	v_mfma_f32_16x16x4_f32 v[100:103], v51, v213, v[100:103]
	v_mfma_f32_16x16x4_f32 v[96:99], v52, v214, v[96:99]
	v_mfma_f32_16x16x4_f32 v[100:103], v53, v215, v[100:103]
	ds_read_b128 v[46:49], v169 offset:25728
	ds_read_b128 v[50:53], v169 offset:25792
	s_waitcnt lgkmcnt(4)
	v_mul_f32_e32 v240, v238, v95
	v_pk_mul_f32 v[76:77], v[72:73], v[238:239] op_sel_hi:[1,0]
	v_pk_mul_f32 v[78:79], v[74:75], v[238:239] op_sel_hi:[1,0]
	v_rcp_f32_e32 v88, v240
	v_readfirstlane_b32 s0, v240
	s_nop 3
	v_pk_add_f32 v[96:97], v[96:97], v[100:101]
	v_pk_add_f32 v[98:99], v[98:99], v[102:103]
	v_pk_fma_f32 v[80:81], v[76:77], v[96:97], v[70:71]
	v_pk_mul_f32 v[110:111], v[78:79], v[98:99]
	s_nop 1
	v_mfma_f32_16x16x4_f32 v[82:85], v93, v80, v[108:111]
	v_mfma_f32_16x16x4_f32 v[82:85], v90, v81, v[82:85]
	s_cmp_lt_u32 s0, 0x2b800000
	s_cbranch_scc0 .Lgdn_nomat_5
	v_pk_mul_f32 v[184:185], v[184:185], v[240:241] op_sel_hi:[1,0]
	v_pk_mul_f32 v[186:187], v[186:187], v[240:241] op_sel_hi:[1,0]
	v_pk_mul_f32 v[188:189], v[188:189], v[240:241] op_sel_hi:[1,0]
	v_pk_mul_f32 v[190:191], v[190:191], v[240:241] op_sel_hi:[1,0]
	v_pk_mul_f32 v[192:193], v[192:193], v[240:241] op_sel_hi:[1,0]
	v_pk_mul_f32 v[194:195], v[194:195], v[240:241] op_sel_hi:[1,0]
	v_pk_mul_f32 v[196:197], v[196:197], v[240:241] op_sel_hi:[1,0]
	v_pk_mul_f32 v[198:199], v[198:199], v[240:241] op_sel_hi:[1,0]
	v_pk_mul_f32 v[200:201], v[200:201], v[240:241] op_sel_hi:[1,0]
	v_pk_mul_f32 v[202:203], v[202:203], v[240:241] op_sel_hi:[1,0]
	v_pk_mul_f32 v[204:205], v[204:205], v[240:241] op_sel_hi:[1,0]
	v_pk_mul_f32 v[206:207], v[206:207], v[240:241] op_sel_hi:[1,0]
	v_pk_mul_f32 v[208:209], v[208:209], v[240:241] op_sel_hi:[1,0]
	v_pk_mul_f32 v[210:211], v[210:211], v[240:241] op_sel_hi:[1,0]
	v_pk_mul_f32 v[212:213], v[212:213], v[240:241] op_sel_hi:[1,0]
	v_pk_mul_f32 v[214:215], v[214:215], v[240:241] op_sel_hi:[1,0]
	v_mov_b32_e32 v240, 1.0
	v_mov_b32_e32 v88, 1.0
.Lgdn_nomat_5:
	v_mov_b32_e32 v238, v240
	s_nop 7
	v_pk_mul_f32 v[86:87], v[82:83], v[88:89] op_sel_hi:[1,0]
	s_nop 1
	v_mfma_f32_16x16x4_f32 v[184:187], v54, v86, v[184:187]
	v_mfma_f32_16x16x4_f32 v[188:191], v55, v86, v[188:191]
	v_mfma_f32_16x16x4_f32 v[192:195], v56, v86, v[192:195]
	v_mfma_f32_16x16x4_f32 v[196:199], v57, v86, v[196:199]
	v_mfma_f32_16x16x4_f32 v[200:203], v58, v86, v[200:203]
	v_mfma_f32_16x16x4_f32 v[204:207], v59, v86, v[204:207]
	v_mfma_f32_16x16x4_f32 v[208:211], v60, v86, v[208:211]
	v_mfma_f32_16x16x4_f32 v[212:215], v61, v86, v[212:215]
	v_mfma_f32_16x16x4_f32 v[184:187], v62, v87, v[184:187]
	v_mfma_f32_16x16x4_f32 v[188:191], v63, v87, v[188:191]
	v_mfma_f32_16x16x4_f32 v[192:195], v64, v87, v[192:195]
	v_mfma_f32_16x16x4_f32 v[196:199], v65, v87, v[196:199]
	v_mfma_f32_16x16x4_f32 v[200:203], v66, v87, v[200:203]
	v_mfma_f32_16x16x4_f32 v[204:207], v67, v87, v[204:207]
	v_mfma_f32_16x16x4_f32 v[208:211], v68, v87, v[208:211]
	v_mfma_f32_16x16x4_f32 v[212:215], v69, v87, v[212:215]
	ds_write2st64_b32 v172, v84, v85 offset0:40 offset1:44
	s_mov_b64 exec, s[40:41]
	ds_add_u32 v91, v92 offset:20
	s_mov_b64 exec, -1
	s_waitcnt lgkmcnt(2)
	v_mfma_f32_16x16x4_f32 v[96:99], v22, v184, 0
	v_mfma_f32_16x16x4_f32 v[100:103], v23, v185, 0
	v_mfma_f32_16x16x4_f32 v[96:99], v24, v186, v[96:99]
	v_mfma_f32_16x16x4_f32 v[100:103], v25, v187, v[100:103]
	ds_read_b32 v54, v170 offset:25344
	ds_read_b32 v55, v170 offset:25408
	ds_read_b32 v56, v170 offset:25472
	ds_read_b32 v57, v170 offset:25536
	v_mfma_f32_16x16x4_f32 v[96:99], v26, v188, v[96:99]
	v_mfma_f32_16x16x4_f32 v[100:103], v27, v189, v[100:103]
	v_mfma_f32_16x16x4_f32 v[96:99], v28, v190, v[96:99]
	v_mfma_f32_16x16x4_f32 v[100:103], v29, v191, v[100:103]
	ds_read_b128 v[22:25], v169 offset:29568
	ds_read_b32 v58, v170 offset:25600
	ds_read_b32 v59, v170 offset:25664
	ds_read_b32 v60, v170 offset:25728
	ds_read_b32 v61, v170 offset:25792
	v_mfma_f32_16x16x4_f32 v[96:99], v30, v192, v[96:99]
	v_mfma_f32_16x16x4_f32 v[100:103], v31, v193, v[100:103]
	v_mfma_f32_16x16x4_f32 v[96:99], v32, v194, v[96:99]
	v_mfma_f32_16x16x4_f32 v[100:103], v33, v195, v[100:103]
	ds_read_b128 v[26:29], v169 offset:29632
	ds_read_b32 v62, v170 offset:27456
	ds_read_b32 v63, v170 offset:27520
	ds_read_b32 v64, v170 offset:27584
	ds_read_b32 v65, v170 offset:27648
	v_mfma_f32_16x16x4_f32 v[96:99], v34, v196, v[96:99]
	v_mfma_f32_16x16x4_f32 v[100:103], v35, v197, v[100:103]
	v_mfma_f32_16x16x4_f32 v[96:99], v36, v198, v[96:99]
	v_mfma_f32_16x16x4_f32 v[100:103], v37, v199, v[100:103]
	ds_read_b128 v[30:33], v169 offset:29696
	ds_read_b32 v66, v170 offset:27712
	ds_read_b32 v67, v170 offset:27776
	ds_read_b32 v68, v170 offset:27840
	ds_read_b32 v69, v170 offset:27904
	v_mfma_f32_16x16x4_f32 v[96:99], v38, v200, v[96:99]
	v_mfma_f32_16x16x4_f32 v[100:103], v39, v201, v[100:103]
	v_mfma_f32_16x16x4_f32 v[96:99], v40, v202, v[96:99]
	v_mfma_f32_16x16x4_f32 v[100:103], v41, v203, v[100:103]
	ds_read_b128 v[34:37], v169 offset:29760
	ds_read_b32 v95, v175 offset:476
	ds_read2_b32 v[72:73], v174 offset0:48 offset1:52
	ds_read2_b32 v[74:75], v176 offset0:48 offset1:52
	ds_read2st64_b32 v[70:71], v171 offset0:48 offset1:52
	ds_read_b32 v93, v173 offset:3072
	ds_read_b32 v90, v173 offset:3088
	v_mfma_f32_16x16x4_f32 v[96:99], v42, v204, v[96:99]
	v_mfma_f32_16x16x4_f32 v[100:103], v43, v205, v[100:103]
	v_mfma_f32_16x16x4_f32 v[96:99], v44, v206, v[96:99]
	v_mfma_f32_16x16x4_f32 v[100:103], v45, v207, v[100:103]
	ds_read_b128 v[38:41], v169 offset:29824
	v_mfma_f32_16x16x4_f32 v[96:99], v46, v208, v[96:99]
	v_mfma_f32_16x16x4_f32 v[100:103], v47, v209, v[100:103]
	v_mfma_f32_16x16x4_f32 v[96:99], v48, v210, v[96:99]
	v_mfma_f32_16x16x4_f32 v[100:103], v49, v211, v[100:103]
	ds_read_b128 v[42:45], v169 offset:29888
	v_mfma_f32_16x16x4_f32 v[96:99], v50, v212, v[96:99]
	v_mfma_f32_16x16x4_f32 v[100:103], v51, v213, v[100:103]
	v_mfma_f32_16x16x4_f32 v[96:99], v52, v214, v[96:99]
	v_mfma_f32_16x16x4_f32 v[100:103], v53, v215, v[100:103]
	ds_read_b128 v[46:49], v169 offset:29952
	ds_read_b128 v[50:53], v169 offset:30016
	s_waitcnt lgkmcnt(4)
	v_mul_f32_e32 v240, v238, v95
	v_pk_mul_f32 v[76:77], v[72:73], v[238:239] op_sel_hi:[1,0]
	v_pk_mul_f32 v[78:79], v[74:75], v[238:239] op_sel_hi:[1,0]
	v_rcp_f32_e32 v88, v240
	v_readfirstlane_b32 s0, v240
	s_nop 3
	v_pk_add_f32 v[96:97], v[96:97], v[100:101]
	v_pk_add_f32 v[98:99], v[98:99], v[102:103]
	v_pk_fma_f32 v[80:81], v[76:77], v[96:97], v[70:71]
	v_pk_mul_f32 v[110:111], v[78:79], v[98:99]
	s_nop 1
	v_mfma_f32_16x16x4_f32 v[82:85], v93, v80, v[108:111]
	v_mfma_f32_16x16x4_f32 v[82:85], v90, v81, v[82:85]
	s_cmp_lt_u32 s0, 0x2b800000
	s_cbranch_scc0 .Lgdn_nomat_6
	v_pk_mul_f32 v[184:185], v[184:185], v[240:241] op_sel_hi:[1,0]
	v_pk_mul_f32 v[186:187], v[186:187], v[240:241] op_sel_hi:[1,0]
	v_pk_mul_f32 v[188:189], v[188:189], v[240:241] op_sel_hi:[1,0]
	v_pk_mul_f32 v[190:191], v[190:191], v[240:241] op_sel_hi:[1,0]
	v_pk_mul_f32 v[192:193], v[192:193], v[240:241] op_sel_hi:[1,0]
	v_pk_mul_f32 v[194:195], v[194:195], v[240:241] op_sel_hi:[1,0]
	v_pk_mul_f32 v[196:197], v[196:197], v[240:241] op_sel_hi:[1,0]
	v_pk_mul_f32 v[198:199], v[198:199], v[240:241] op_sel_hi:[1,0]
	v_pk_mul_f32 v[200:201], v[200:201], v[240:241] op_sel_hi:[1,0]
	v_pk_mul_f32 v[202:203], v[202:203], v[240:241] op_sel_hi:[1,0]
	v_pk_mul_f32 v[204:205], v[204:205], v[240:241] op_sel_hi:[1,0]
	v_pk_mul_f32 v[206:207], v[206:207], v[240:241] op_sel_hi:[1,0]
	v_pk_mul_f32 v[208:209], v[208:209], v[240:241] op_sel_hi:[1,0]
	v_pk_mul_f32 v[210:211], v[210:211], v[240:241] op_sel_hi:[1,0]
	v_pk_mul_f32 v[212:213], v[212:213], v[240:241] op_sel_hi:[1,0]
	v_pk_mul_f32 v[214:215], v[214:215], v[240:241] op_sel_hi:[1,0]
	v_mov_b32_e32 v240, 1.0
	v_mov_b32_e32 v88, 1.0
.Lgdn_nomat_6:
	v_mov_b32_e32 v238, v240
	s_nop 7
	v_pk_mul_f32 v[86:87], v[82:83], v[88:89] op_sel_hi:[1,0]
	s_nop 1
	v_mfma_f32_16x16x4_f32 v[184:187], v54, v86, v[184:187]
	v_mfma_f32_16x16x4_f32 v[188:191], v55, v86, v[188:191]
	v_mfma_f32_16x16x4_f32 v[192:195], v56, v86, v[192:195]
	v_mfma_f32_16x16x4_f32 v[196:199], v57, v86, v[196:199]
	v_mfma_f32_16x16x4_f32 v[200:203], v58, v86, v[200:203]
	v_mfma_f32_16x16x4_f32 v[204:207], v59, v86, v[204:207]
	v_mfma_f32_16x16x4_f32 v[208:211], v60, v86, v[208:211]
	v_mfma_f32_16x16x4_f32 v[212:215], v61, v86, v[212:215]
	v_mfma_f32_16x16x4_f32 v[184:187], v62, v87, v[184:187]
	v_mfma_f32_16x16x4_f32 v[188:191], v63, v87, v[188:191]
	v_mfma_f32_16x16x4_f32 v[192:195], v64, v87, v[192:195]
	v_mfma_f32_16x16x4_f32 v[196:199], v65, v87, v[196:199]
	v_mfma_f32_16x16x4_f32 v[200:203], v66, v87, v[200:203]
	v_mfma_f32_16x16x4_f32 v[204:207], v67, v87, v[204:207]
	v_mfma_f32_16x16x4_f32 v[208:211], v68, v87, v[208:211]
	v_mfma_f32_16x16x4_f32 v[212:215], v69, v87, v[212:215]
	ds_write2st64_b32 v172, v84, v85 offset0:48 offset1:52
	s_mov_b64 exec, s[40:41]
	ds_add_u32 v91, v92 offset:24
	s_mov_b64 exec, -1
	s_waitcnt lgkmcnt(2)
	v_mfma_f32_16x16x4_f32 v[96:99], v22, v184, 0
	v_mfma_f32_16x16x4_f32 v[100:103], v23, v185, 0
	v_mfma_f32_16x16x4_f32 v[96:99], v24, v186, v[96:99]
	v_mfma_f32_16x16x4_f32 v[100:103], v25, v187, v[100:103]
	ds_read_b32 v54, v170 offset:29568
	ds_read_b32 v55, v170 offset:29632
	ds_read_b32 v56, v170 offset:29696
	ds_read_b32 v57, v170 offset:29760
	v_mfma_f32_16x16x4_f32 v[96:99], v26, v188, v[96:99]
	v_mfma_f32_16x16x4_f32 v[100:103], v27, v189, v[100:103]
	v_mfma_f32_16x16x4_f32 v[96:99], v28, v190, v[96:99]
	v_mfma_f32_16x16x4_f32 v[100:103], v29, v191, v[100:103]
	ds_read_b128 v[22:25], v169 offset:33792
	ds_read_b32 v58, v170 offset:29824
	ds_read_b32 v59, v170 offset:29888
	ds_read_b32 v60, v170 offset:29952
	ds_read_b32 v61, v170 offset:30016
	v_mfma_f32_16x16x4_f32 v[96:99], v30, v192, v[96:99]
	v_mfma_f32_16x16x4_f32 v[100:103], v31, v193, v[100:103]
	v_mfma_f32_16x16x4_f32 v[96:99], v32, v194, v[96:99]
	v_mfma_f32_16x16x4_f32 v[100:103], v33, v195, v[100:103]
	ds_read_b128 v[26:29], v169 offset:33856
	ds_read_b32 v62, v170 offset:31680
	ds_read_b32 v63, v170 offset:31744
	ds_read_b32 v64, v170 offset:31808
	ds_read_b32 v65, v170 offset:31872
	v_mfma_f32_16x16x4_f32 v[96:99], v34, v196, v[96:99]
	v_mfma_f32_16x16x4_f32 v[100:103], v35, v197, v[100:103]
	v_mfma_f32_16x16x4_f32 v[96:99], v36, v198, v[96:99]
	v_mfma_f32_16x16x4_f32 v[100:103], v37, v199, v[100:103]
	ds_read_b128 v[30:33], v169 offset:33920
	ds_read_b32 v66, v170 offset:31936
	ds_read_b32 v67, v170 offset:32000
	ds_read_b32 v68, v170 offset:32064
	ds_read_b32 v69, v170 offset:32128
	v_mfma_f32_16x16x4_f32 v[96:99], v38, v200, v[96:99]
	v_mfma_f32_16x16x4_f32 v[100:103], v39, v201, v[100:103]
	v_mfma_f32_16x16x4_f32 v[96:99], v40, v202, v[96:99]
	v_mfma_f32_16x16x4_f32 v[100:103], v41, v203, v[100:103]
	ds_read_b128 v[34:37], v169 offset:33984
	ds_read_b32 v95, v175 offset:508
	ds_read2_b32 v[72:73], v174 offset0:56 offset1:60
	ds_read2_b32 v[74:75], v176 offset0:56 offset1:60
	ds_read2st64_b32 v[70:71], v171 offset0:56 offset1:60
	ds_read_b32 v93, v173 offset:3584
	ds_read_b32 v90, v173 offset:3600
	v_mfma_f32_16x16x4_f32 v[96:99], v42, v204, v[96:99]
	v_mfma_f32_16x16x4_f32 v[100:103], v43, v205, v[100:103]
	v_mfma_f32_16x16x4_f32 v[96:99], v44, v206, v[96:99]
	v_mfma_f32_16x16x4_f32 v[100:103], v45, v207, v[100:103]
	ds_read_b128 v[38:41], v169 offset:34048
	v_mfma_f32_16x16x4_f32 v[96:99], v46, v208, v[96:99]
	v_mfma_f32_16x16x4_f32 v[100:103], v47, v209, v[100:103]
	v_mfma_f32_16x16x4_f32 v[96:99], v48, v210, v[96:99]
	v_mfma_f32_16x16x4_f32 v[100:103], v49, v211, v[100:103]
	ds_read_b128 v[42:45], v169 offset:34112
	v_mfma_f32_16x16x4_f32 v[96:99], v50, v212, v[96:99]
	v_mfma_f32_16x16x4_f32 v[100:103], v51, v213, v[100:103]
	v_mfma_f32_16x16x4_f32 v[96:99], v52, v214, v[96:99]
	v_mfma_f32_16x16x4_f32 v[100:103], v53, v215, v[100:103]
	ds_read_b128 v[46:49], v169 offset:34176
	ds_read_b128 v[50:53], v169 offset:34240
	s_waitcnt lgkmcnt(4)
	v_mul_f32_e32 v240, v238, v95
	v_pk_mul_f32 v[76:77], v[72:73], v[238:239] op_sel_hi:[1,0]
	v_pk_mul_f32 v[78:79], v[74:75], v[238:239] op_sel_hi:[1,0]
	v_rcp_f32_e32 v88, v240
	v_readfirstlane_b32 s0, v240
	s_nop 3
	v_pk_add_f32 v[96:97], v[96:97], v[100:101]
	v_pk_add_f32 v[98:99], v[98:99], v[102:103]
	v_pk_fma_f32 v[80:81], v[76:77], v[96:97], v[70:71]
	v_pk_mul_f32 v[110:111], v[78:79], v[98:99]
	s_nop 1
	v_mfma_f32_16x16x4_f32 v[82:85], v93, v80, v[108:111]
	v_mfma_f32_16x16x4_f32 v[82:85], v90, v81, v[82:85]
	s_cmp_lt_u32 s0, 0x2b800000
	s_cbranch_scc0 .Lgdn_nomat_7
	v_pk_mul_f32 v[184:185], v[184:185], v[240:241] op_sel_hi:[1,0]
	v_pk_mul_f32 v[186:187], v[186:187], v[240:241] op_sel_hi:[1,0]
	v_pk_mul_f32 v[188:189], v[188:189], v[240:241] op_sel_hi:[1,0]
	v_pk_mul_f32 v[190:191], v[190:191], v[240:241] op_sel_hi:[1,0]
	v_pk_mul_f32 v[192:193], v[192:193], v[240:241] op_sel_hi:[1,0]
	v_pk_mul_f32 v[194:195], v[194:195], v[240:241] op_sel_hi:[1,0]
	v_pk_mul_f32 v[196:197], v[196:197], v[240:241] op_sel_hi:[1,0]
	v_pk_mul_f32 v[198:199], v[198:199], v[240:241] op_sel_hi:[1,0]
	v_pk_mul_f32 v[200:201], v[200:201], v[240:241] op_sel_hi:[1,0]
	v_pk_mul_f32 v[202:203], v[202:203], v[240:241] op_sel_hi:[1,0]
	v_pk_mul_f32 v[204:205], v[204:205], v[240:241] op_sel_hi:[1,0]
	v_pk_mul_f32 v[206:207], v[206:207], v[240:241] op_sel_hi:[1,0]
	v_pk_mul_f32 v[208:209], v[208:209], v[240:241] op_sel_hi:[1,0]
	v_pk_mul_f32 v[210:211], v[210:211], v[240:241] op_sel_hi:[1,0]
	v_pk_mul_f32 v[212:213], v[212:213], v[240:241] op_sel_hi:[1,0]
	v_pk_mul_f32 v[214:215], v[214:215], v[240:241] op_sel_hi:[1,0]
	v_mov_b32_e32 v240, 1.0
	v_mov_b32_e32 v88, 1.0
.Lgdn_nomat_7:
	v_mov_b32_e32 v238, v240
	s_nop 7
	v_pk_mul_f32 v[86:87], v[82:83], v[88:89] op_sel_hi:[1,0]
	s_nop 1
	v_mfma_f32_16x16x4_f32 v[184:187], v54, v86, v[184:187]
	v_mfma_f32_16x16x4_f32 v[188:191], v55, v86, v[188:191]
	v_mfma_f32_16x16x4_f32 v[192:195], v56, v86, v[192:195]
	v_mfma_f32_16x16x4_f32 v[196:199], v57, v86, v[196:199]
	v_mfma_f32_16x16x4_f32 v[200:203], v58, v86, v[200:203]
	v_mfma_f32_16x16x4_f32 v[204:207], v59, v86, v[204:207]
	v_mfma_f32_16x16x4_f32 v[208:211], v60, v86, v[208:211]
	v_mfma_f32_16x16x4_f32 v[212:215], v61, v86, v[212:215]
	v_mfma_f32_16x16x4_f32 v[184:187], v62, v87, v[184:187]
	v_mfma_f32_16x16x4_f32 v[188:191], v63, v87, v[188:191]
	v_mfma_f32_16x16x4_f32 v[192:195], v64, v87, v[192:195]
	v_mfma_f32_16x16x4_f32 v[196:199], v65, v87, v[196:199]
	v_mfma_f32_16x16x4_f32 v[200:203], v66, v87, v[200:203]
	v_mfma_f32_16x16x4_f32 v[204:207], v67, v87, v[204:207]
	v_mfma_f32_16x16x4_f32 v[208:211], v68, v87, v[208:211]
	v_mfma_f32_16x16x4_f32 v[212:215], v69, v87, v[212:215]
	ds_write2st64_b32 v172, v84, v85 offset0:56 offset1:60
	s_mov_b64 exec, s[40:41]
	ds_add_u32 v91, v92 offset:28
	s_mov_b64 exec, -1
	s_branch .Lgdn_done
